# ffn_act: in-loop wait for pre-loop loads moved to the loop pre-header so a row block's 16 loads issue together
# baseline (speedup 1.0000x reference)
; DI unsigned pack2(float lo, float hi) { f32x2 v = {lo, hi}; bf2_t b = __builtin_convertvector(v, bf2_t); return __builtin_bit_cast(unsigned, b); }
; DI void unpack8(const u32x4& v, float* f) { f[0] = bflo(v.x); f[1] = bfhi(v.x); f[2] = bflo(v.y); f[3] = bfhi(v.y); f[4] = bflo(v.z); f[5] = bfhi(v.z); f[6] = bflo(v.w); f[7] = bfhi(v.w); }
; DI float gelu_tanh(float x) { const float y = 0.7978845608028654f * (x + 0.044715f * x * x * x); const float t = 1.f - 2.f * __builtin_amdgcn_rcpf(1.f + __expf(2.f * y)); return 0.5f * x * (1.f + t); }
; DI void ffn_act_phase(const Params& P, int l) {
;     ...
;     for (int rb = 0; rb < 4; ++rb) {
;       u32x4 G[8], U[8];
; #pragma unroll
;       for (int i = 0; i < 8; ++i) { const size_t ro = (size_t)(r0 + rb * 8 + i) * DFF2 + ch; G[i] = __builtin_nontemporal_load((const u32x4*)(u + ro)); U[i] = __builtin_nontemporal_load((const u32x4*)(u + ro + DFF)); }
; #pragma unroll
;       for (int i = 0; i < 8; ++i) {
;         float g0[8], u0[8]; unpack8(G[i], g0); unpack8(U[i], u0);
;         float o[8];
; #pragma unroll
;         for (int e = 0; e < 8; ++e) { const float yg = wg[0][e] * g2[e] + wg[1][e] * g1[e] + wg[2][e] * g0[e] + bg[e]; const float yu = wu[0][e] * u2[e] + wu[1][e] * u1[e] + wu[2][e] * u0[e] + bu[e];
;           o[e] = gelu_tanh(yg) * yu; g2[e] = g1[e]; g1[e] = g0[e]; u2[e] = u1[e]; u1[e] = u0[e]; }
;         u32x4 pk = {pack2(o[0], o[1]), pack2(o[2], o[3]), pack2(o[4], o[5]), pack2(o[6], o[7])};
;         *(u32x4*)(act + (size_t)(r0 + rb * 8 + i) * DFF + ch) = pk;
;       }
.LBB0_1020:
	s_or_b64 exec, exec, s[22:23]
	v_mad_i64_i32 v[160:161], s[22:23], v66, s81, v[130:131]
	s_movk_i32 s22, 0x5800
	s_nop 0
	v_mad_i64_i32 v[162:163], s[22:23], v66, s22, v[130:131]
	s_mov_b32 s22, 4
	s_waitcnt vmcnt(0) lgkmcnt(0)
.LBB0_1021:
	v_lshl_add_u64 v[70:71], v[162:163], 0, v[138:139]
	s_mov_b32 s23, 0x122e8000
	v_add_co_u32_e32 v66, vcc, s23, v70
	s_mov_b32 s23, 0x122ed000
	s_nop 0
	v_addc_co_u32_e32 v67, vcc, 0, v71, vcc
	global_load_dwordx4 v[82:85], v[66:67], off nt
	v_add_co_u32_e32 v66, vcc, s85, v70
	s_nop 0
	v_pk_mul_f32 v[192:193], v[4:5], v[168:169]
	v_addc_co_u32_e32 v67, vcc, 0, v71, vcc
	global_load_dwordx4 v[86:89], v[66:67], off offset:3072 nt
	v_add_co_u32_e32 v66, vcc, s23, v70
	s_mov_b32 s23, 0x122f0000
	s_nop 0
	v_addc_co_u32_e32 v67, vcc, 0, v71, vcc
	global_load_dwordx4 v[106:109], v[66:67], off offset:2048 nt
	v_add_co_u32_e32 v66, vcc, s23, v70
	s_mov_b32 s23, 0x122f3000
	s_nop 0
	v_addc_co_u32_e32 v67, vcc, 0, v71, vcc
	global_load_dwordx4 v[110:113], v[66:67], off offset:1024 nt
	v_add_co_u32_e32 v66, vcc, s23, v70
	s_mov_b32 s23, 0x122f5000
	s_nop 0
	v_addc_co_u32_e32 v67, vcc, 0, v71, vcc
	global_load_dwordx4 v[114:117], v[66:67], off nt
	v_add_co_u32_e32 v66, vcc, s23, v70
	s_mov_b32 s23, 0x122f8000
	s_nop 0
	v_addc_co_u32_e32 v67, vcc, 0, v71, vcc
	global_load_dwordx4 v[118:121], v[66:67], off offset:3072 nt
	v_add_co_u32_e32 v66, vcc, s23, v70
	s_mov_b32 s23, 0x122fb000
	s_nop 0
	v_addc_co_u32_e32 v67, vcc, 0, v71, vcc
	global_load_dwordx4 v[122:125], v[66:67], off offset:2048 nt
	v_add_co_u32_e32 v66, vcc, s23, v70
	v_pk_mul_f32 v[200:201], v[2:3], v[166:167]
	s_nop 0
	v_addc_co_u32_e32 v67, vcc, 0, v71, vcc
	global_load_dwordx4 v[126:129], v[66:67], off offset:1024 nt
	s_mov_b32 s23, 0x122fe000
	v_add_co_u32_e32 v66, vcc, s23, v70
	s_mov_b32 s23, 0x12300000
	s_nop 0
	v_addc_co_u32_e32 v67, vcc, 0, v71, vcc
	global_load_dwordx4 v[98:101], v[66:67], off nt
	v_add_co_u32_e32 v66, vcc, s23, v70
	s_mov_b32 s23, 0x12303000
	s_nop 0
	v_addc_co_u32_e32 v67, vcc, 0, v71, vcc
	global_load_dwordx4 v[102:105], v[66:67], off offset:3072 nt
	v_add_co_u32_e32 v66, vcc, s23, v70
	s_mov_b32 s23, 0x12306000
	s_nop 0
	v_addc_co_u32_e32 v67, vcc, 0, v71, vcc
	global_load_dwordx4 v[90:93], v[66:67], off offset:2048 nt
	v_add_co_u32_e32 v66, vcc, s23, v70
	s_mov_b32 s23, 0x12309000
	s_nop 0
	v_addc_co_u32_e32 v67, vcc, 0, v71, vcc
	global_load_dwordx4 v[94:97], v[66:67], off offset:1024 nt
	v_add_co_u32_e32 v66, vcc, s23, v70
	s_mov_b32 s23, 0x1230b000
	s_nop 0
	v_addc_co_u32_e32 v67, vcc, 0, v71, vcc
	global_load_dwordx4 v[74:77], v[66:67], off nt
	v_add_co_u32_e32 v66, vcc, s23, v70
	s_mov_b32 s23, 0x1230e000
	s_nop 0
	v_addc_co_u32_e32 v67, vcc, 0, v71, vcc
	global_load_dwordx4 v[78:81], v[66:67], off offset:3072 nt
	v_add_co_u32_e32 v66, vcc, s23, v70
	s_mov_b32 s23, 0x12311000
	s_nop 0
	v_addc_co_u32_e32 v67, vcc, 0, v71, vcc
	v_add_co_u32_e32 v70, vcc, s23, v70
	v_lshl_add_u64 v[176:177], v[160:161], 0, v[138:139]
	s_nop 0
	v_addc_co_u32_e32 v71, vcc, 0, v71, vcc
	s_mov_b32 s23, 0x62f0000
	global_load_dwordx4 v[66:69], v[66:67], off offset:2048 nt
	s_waitcnt vmcnt(0) lgkmcnt(0)
	v_lshlrev_b32_e32 v194, 16, v106
	v_and_b32_e32 v195, 0xffff0000, v106
	global_load_dwordx4 v[70:73], v[70:71], off offset:1024 nt
	v_mov_b32_e32 v156, v141
	v_mov_b32_e32 v141, v159
	v_pk_fma_f32 v[192:193], v[20:21], v[148:149], v[192:193]
	v_lshlrev_b32_e32 v198, 16, v110
	v_and_b32_e32 v199, 0xffff0000, v110
	v_lshlrev_b32_e32 v190, 16, v111
	v_and_b32_e32 v191, 0xffff0000, v111
	v_pk_mul_f32 v[186:187], v[28:29], v[152:153]
	v_pk_mul_f32 v[182:183], v[6:7], v[174:175]
	v_lshlrev_b32_e32 v196, 16, v114
	v_and_b32_e32 v197, 0xffff0000, v114
	v_pk_mul_f32 v[168:169], v[18:19], v[196:197]
	v_pk_fma_f32 v[144:145], v[12:13], v[144:145], v[186:187]
	v_pk_fma_f32 v[168:169], v[2:3], v[194:195], v[168:169]
	v_pk_mul_f32 v[174:175], v[30:31], v[154:155]
	v_lshlrev_b32_e32 v166, 16, v118
	v_and_b32_e32 v167, 0xffff0000, v118
	v_pk_mul_f32 v[188:189], v[26:27], v[166:167]
	v_lshlrev_b32_e32 v118, 16, v108
	v_pk_fma_f32 v[188:189], v[10:11], v[198:199], v[188:189]
	v_pk_mul_f32 v[180:181], v[8:9], v[178:179]
	v_lshlrev_b32_e32 v212, 16, v122
	v_and_b32_e32 v213, 0xffff0000, v122
	v_pk_fma_f32 v[168:169], v[34:35], v[212:213], v[168:169]
	v_lshlrev_b32_e32 v224, 16, v123
	v_pk_add_f32 v[168:169], v[50:51], v[168:169]
	v_and_b32_e32 v225, 0xffff0000, v123
	v_mul_f32_e32 v0, 0x3d372713, v168
	v_mul_f32_e32 v0, v168, v0
	v_fma_f32 v0, v168, v0, v168
	v_mul_f32_e32 v0, 0x3f4c422a, v0
	v_add_f32_e32 v0, v0, v0
	v_mul_f32_e32 v0, 0x3fb8aa3b, v0
	v_exp_f32_e32 v0, v0
	v_lshlrev_b32_e32 v202, 16, v126
	v_and_b32_e32 v203, 0xffff0000, v126
	v_pk_fma_f32 v[188:189], v[42:43], v[202:203], v[188:189]
	v_add_f32_e32 v0, 1.0, v0
	v_rcp_f32_e32 v184, v0
	v_mul_f32_e32 v0, 0x3d372713, v169
	v_mul_f32_e32 v0, v169, v0
	v_fma_f32 v0, v169, v0, v169
	v_mul_f32_e32 v0, 0x3f4c422a, v0
	v_add_f32_e32 v0, v0, v0
	v_mul_f32_e32 v0, 0x3fb8aa3b, v0
	v_exp_f32_e32 v0, v0
	v_pk_mul_f32 v[168:169], v[168:169], 0.5 op_sel_hi:[1,0]
	v_pk_add_f32 v[188:189], v[58:59], v[188:189]
	v_lshlrev_b32_e32 v220, 16, v127
	v_add_f32_e32 v0, 1.0, v0
	v_rcp_f32_e32 v185, v0
	v_and_b32_e32 v221, 0xffff0000, v127
	v_lshlrev_b32_e32 v122, 16, v116
	v_and_b32_e32 v123, 0xffff0000, v116
	v_pk_fma_f32 v[184:185], v[184:185], 2.0, 1.0 op_sel_hi:[1,0,0] neg_lo:[1,0,0] neg_hi:[1,0,0]
	v_lshlrev_b32_e32 v228, 16, v124
	v_pk_add_f32 v[184:185], v[184:185], 1.0 op_sel_hi:[1,0]
	v_and_b32_e32 v229, 0xffff0000, v124
	v_pk_mul_f32 v[168:169], v[168:169], v[184:185]
	v_lshlrev_b32_e32 v184, 16, v107
; DI unsigned pack2(float lo, float hi) { f32x2 v = {lo, hi}; bf2_t b = __builtin_convertvector(v, bf2_t); return __builtin_bit_cast(unsigned, b); }
; DI void unpack8(const u32x4& v, float* f) { f[0] = bflo(v.x); f[1] = bfhi(v.x); f[2] = bflo(v.y); f[3] = bfhi(v.y); f[4] = bflo(v.z); f[5] = bfhi(v.z); f[6] = bflo(v.w); f[7] = bfhi(v.w); }
; DI float gelu_tanh(float x) { const float y = 0.7978845608028654f * (x + 0.044715f * x * x * x); const float t = 1.f - 2.f * __builtin_amdgcn_rcpf(1.f + __expf(2.f * y)); return 0.5f * x * (1.f + t); }
; DI void ffn_act_phase(const Params& P, int l) {
;     ...
;       for (int i = 0; i < 8; ++i) {
;         float g0[8], u0[8]; unpack8(G[i], g0); unpack8(U[i], u0);
;         float o[8];
; #pragma unroll
;         for (int e = 0; e < 8; ++e) { const float yg = wg[0][e] * g2[e] + wg[1][e] * g1[e] + wg[2][e] * g0[e] + bg[e]; const float yu = wu[0][e] * u2[e] + wu[1][e] * u1[e] + wu[2][e] * u0[e] + bu[e];
;           o[e] = gelu_tanh(yg) * yu; g2[e] = g1[e]; g1[e] = g0[e]; u2[e] = u1[e]; u1[e] = u0[e]; }
;         u32x4 pk = {pack2(o[0], o[1]), pack2(o[2], o[3]), pack2(o[4], o[5]), pack2(o[6], o[7])};
;         *(u32x4*)(act + (size_t)(r0 + rb * 8 + i) * DFF + ch) = pk;
	v_pk_mul_f32 v[204:205], v[188:189], v[168:169]
	v_lshlrev_b32_e32 v188, 16, v115
	v_and_b32_e32 v189, 0xffff0000, v115
	v_and_b32_e32 v185, 0xffff0000, v107
	v_pk_mul_f32 v[106:107], v[20:21], v[188:189]
	v_lshlrev_b32_e32 v168, 16, v119
	v_pk_fma_f32 v[106:107], v[4:5], v[184:185], v[106:107]
	v_and_b32_e32 v169, 0xffff0000, v119
	v_pk_fma_f32 v[106:107], v[36:37], v[224:225], v[106:107]
	v_pk_mul_f32 v[114:115], v[28:29], v[168:169]
	v_pk_add_f32 v[106:107], v[52:53], v[106:107]
	v_pk_fma_f32 v[114:115], v[12:13], v[190:191], v[114:115]
	v_mul_f32_e32 v0, 0x3d372713, v106
	v_mul_f32_e32 v0, v106, v0
	v_fma_f32 v0, v106, v0, v106
	v_mul_f32_e32 v0, 0x3f4c422a, v0
	v_add_f32_e32 v0, v0, v0
	v_mul_f32_e32 v0, 0x3fb8aa3b, v0
	v_exp_f32_e32 v0, v0
	v_pk_fma_f32 v[114:115], v[44:45], v[220:221], v[114:115]
	v_and_b32_e32 v119, 0xffff0000, v108
	v_pk_add_f32 v[114:115], v[60:61], v[114:115]
	v_add_f32_e32 v0, 1.0, v0
	v_rcp_f32_e32 v110, v0
	v_mul_f32_e32 v0, 0x3d372713, v107
	v_mul_f32_e32 v0, v107, v0
	v_fma_f32 v0, v107, v0, v107
	v_mul_f32_e32 v0, 0x3f4c422a, v0
	v_add_f32_e32 v0, v0, v0
	v_mul_f32_e32 v0, 0x3fb8aa3b, v0
	v_exp_f32_e32 v0, v0
	v_pk_mul_f32 v[106:107], v[106:107], 0.5 op_sel_hi:[1,0]
	v_lshlrev_b32_e32 v108, 16, v109
	v_and_b32_e32 v109, 0xffff0000, v109
	v_add_f32_e32 v0, 1.0, v0
	v_rcp_f32_e32 v111, v0
	v_lshlrev_b32_e32 v230, 16, v125
	v_and_b32_e32 v231, 0xffff0000, v125
	v_lshlrev_b32_e32 v126, 16, v112
	v_pk_fma_f32 v[110:111], v[110:111], 2.0, 1.0 op_sel_hi:[1,0,0] neg_lo:[1,0,0] neg_hi:[1,0,0]
	v_and_b32_e32 v127, 0xffff0000, v112
	v_pk_add_f32 v[110:111], v[110:111], 1.0 op_sel_hi:[1,0]
	v_lshlrev_b32_e32 v222, 16, v128
	v_pk_mul_f32 v[106:107], v[106:107], v[110:111]
	v_and_b32_e32 v223, 0xffff0000, v128
	v_pk_mul_f32 v[210:211], v[114:115], v[106:107]
	v_pk_mul_f32 v[106:107], v[22:23], v[122:123]
	v_lshlrev_b32_e32 v114, 16, v120
	v_pk_fma_f32 v[106:107], v[6:7], v[118:119], v[106:107]
	v_and_b32_e32 v115, 0xffff0000, v120
	v_pk_fma_f32 v[106:107], v[38:39], v[228:229], v[106:107]
	v_pk_mul_f32 v[214:215], v[30:31], v[114:115]
	v_pk_add_f32 v[106:107], v[54:55], v[106:107]
	v_pk_fma_f32 v[214:215], v[14:15], v[126:127], v[214:215]
	v_mul_f32_e32 v0, 0x3d372713, v106
	v_mul_f32_e32 v0, v106, v0
	v_fma_f32 v0, v106, v0, v106
	v_mul_f32_e32 v0, 0x3f4c422a, v0
	v_add_f32_e32 v0, v0, v0
	v_mul_f32_e32 v0, 0x3fb8aa3b, v0
	v_exp_f32_e32 v0, v0
	v_pk_fma_f32 v[214:215], v[46:47], v[222:223], v[214:215]
	v_lshlrev_b32_e32 v112, 16, v113
	v_pk_add_f32 v[214:215], v[62:63], v[214:215]
	v_add_f32_e32 v0, 1.0, v0
	v_rcp_f32_e32 v110, v0
	v_mul_f32_e32 v0, 0x3d372713, v107
	v_mul_f32_e32 v0, v107, v0
	v_fma_f32 v0, v107, v0, v107
	v_mul_f32_e32 v0, 0x3f4c422a, v0
	v_add_f32_e32 v0, v0, v0
	v_mul_f32_e32 v0, 0x3fb8aa3b, v0
	v_exp_f32_e32 v0, v0
	v_pk_mul_f32 v[106:107], v[106:107], 0.5 op_sel_hi:[1,0]
	v_and_b32_e32 v113, 0xffff0000, v113
	v_lshlrev_b32_e32 v226, 16, v129
	v_add_f32_e32 v0, 1.0, v0
	v_rcp_f32_e32 v111, v0
	v_and_b32_e32 v227, 0xffff0000, v129
	v_lshlrev_b32_e32 v128, 16, v99
	v_and_b32_e32 v129, 0xffff0000, v99
	v_pk_fma_f32 v[110:111], v[110:111], 2.0, 1.0 op_sel_hi:[1,0,0] neg_lo:[1,0,0] neg_hi:[1,0,0]
	v_pk_mul_f32 v[218:219], v[30:31], v[222:223]
	v_pk_add_f32 v[110:111], v[110:111], 1.0 op_sel_hi:[1,0]
	v_pk_fma_f32 v[218:219], v[14:15], v[114:115], v[218:219]
	v_pk_mul_f32 v[106:107], v[106:107], v[110:111]
	v_lshlrev_b32_e32 v110, 16, v117
	v_and_b32_e32 v111, 0xffff0000, v117
	v_pk_mul_f32 v[116:117], v[24:25], v[110:111]
	v_pk_mul_f32 v[216:217], v[214:215], v[106:107]
	v_pk_fma_f32 v[116:117], v[8:9], v[108:109], v[116:117]
	v_lshlrev_b32_e32 v106, 16, v121
	v_pk_fma_f32 v[116:117], v[40:41], v[230:231], v[116:117]
	v_and_b32_e32 v107, 0xffff0000, v121
	v_pk_add_f32 v[116:117], v[56:57], v[116:117]
	v_pk_mul_f32 v[124:125], v[32:33], v[106:107]
	v_mul_f32_e32 v0, 0x3d372713, v116
	v_mul_f32_e32 v0, v116, v0
	v_fma_f32 v0, v116, v0, v116
	v_mul_f32_e32 v0, 0x3f4c422a, v0
	v_add_f32_e32 v0, v0, v0
	v_mul_f32_e32 v0, 0x3fb8aa3b, v0
	v_exp_f32_e32 v0, v0
	v_pk_fma_f32 v[124:125], v[16:17], v[112:113], v[124:125]
	v_cvt_pk_bf16_f32 v216, v216, v217
	v_pk_fma_f32 v[124:125], v[48:49], v[226:227], v[124:125]
	v_add_f32_e32 v0, 1.0, v0
	v_rcp_f32_e32 v120, v0
	v_mul_f32_e32 v0, 0x3d372713, v117
	v_mul_f32_e32 v0, v117, v0
	v_fma_f32 v0, v117, v0, v117
	v_mul_f32_e32 v0, 0x3f4c422a, v0
	v_add_f32_e32 v0, v0, v0
	v_mul_f32_e32 v0, 0x3fb8aa3b, v0
	v_exp_f32_e32 v0, v0
	v_pk_mul_f32 v[116:117], v[116:117], 0.5 op_sel_hi:[1,0]
	v_pk_add_f32 v[124:125], v[64:65], v[124:125]
	v_cvt_pk_bf16_f32 v214, v204, v205
	v_add_f32_e32 v0, 1.0, v0
	v_rcp_f32_e32 v121, v0
	v_cvt_pk_bf16_f32 v215, v210, v211
	v_lshlrev_b32_e32 v210, 16, v98
	v_and_b32_e32 v211, 0xffff0000, v98
	v_pk_fma_f32 v[120:121], v[120:121], 2.0, 1.0 op_sel_hi:[1,0,0] neg_lo:[1,0,0] neg_hi:[1,0,0]
	v_pk_mul_f32 v[98:99], v[20:21], v[224:225]
	v_pk_add_f32 v[120:121], v[120:121], 1.0 op_sel_hi:[1,0]
	v_pk_fma_f32 v[98:99], v[4:5], v[188:189], v[98:99]
	v_pk_mul_f32 v[116:117], v[116:117], v[120:121]
	v_pk_fma_f32 v[98:99], v[36:37], v[128:129], v[98:99]
	v_pk_mul_f32 v[116:117], v[124:125], v[116:117]
	v_pk_add_f32 v[98:99], v[52:53], v[98:99]
	v_cvt_pk_bf16_f32 v217, v116, v117
	v_add_co_u32_e32 v116, vcc, s23, v176
	v_lshlrev_b32_e32 v204, 16, v102
	s_nop 0
	v_addc_co_u32_e32 v117, vcc, 0, v177, vcc
	global_store_dwordx4 v[116:117], v[214:217], off offset:1024
	v_pk_mul_f32 v[116:117], v[18:19], v[212:213]
	v_and_b32_e32 v205, 0xffff0000, v102
	v_pk_fma_f32 v[116:117], v[2:3], v[196:197], v[116:117]
	v_pk_mul_f32 v[124:125], v[26:27], v[202:203]
; DI unsigned pack2(float lo, float hi) { f32x2 v = {lo, hi}; bf2_t b = __builtin_convertvector(v, bf2_t); return __builtin_bit_cast(unsigned, b); }
; DI void unpack8(const u32x4& v, float* f) { f[0] = bflo(v.x); f[1] = bfhi(v.x); f[2] = bflo(v.y); f[3] = bfhi(v.y); f[4] = bflo(v.z); f[5] = bfhi(v.z); f[6] = bflo(v.w); f[7] = bfhi(v.w); }
; DI float gelu_tanh(float x) { const float y = 0.7978845608028654f * (x + 0.044715f * x * x * x); const float t = 1.f - 2.f * __builtin_amdgcn_rcpf(1.f + __expf(2.f * y)); return 0.5f * x * (1.f + t); }
; DI void ffn_act_phase(const Params& P, int l) {
;     ...
;       for (int i = 0; i < 8; ++i) {
;         float g0[8], u0[8]; unpack8(G[i], g0); unpack8(U[i], u0);
;         float o[8];
; #pragma unroll
;         for (int e = 0; e < 8; ++e) { const float yg = wg[0][e] * g2[e] + wg[1][e] * g1[e] + wg[2][e] * g0[e] + bg[e]; const float yu = wu[0][e] * u2[e] + wu[1][e] * u1[e] + wu[2][e] * u0[e] + bu[e];
;           o[e] = gelu_tanh(yg) * yu; g2[e] = g1[e]; g1[e] = g0[e]; u2[e] = u1[e]; u1[e] = u0[e]; }
;         u32x4 pk = {pack2(o[0], o[1]), pack2(o[2], o[3]), pack2(o[4], o[5]), pack2(o[6], o[7])};
;         *(u32x4*)(act + (size_t)(r0 + rb * 8 + i) * DFF + ch) = pk;
	v_pk_fma_f32 v[116:117], v[34:35], v[210:211], v[116:117]
	v_pk_fma_f32 v[124:125], v[10:11], v[166:167], v[124:125]
	v_pk_add_f32 v[116:117], v[50:51], v[116:117]
	v_pk_fma_f32 v[124:125], v[42:43], v[204:205], v[124:125]
	v_mul_f32_e32 v0, 0x3d372713, v116
	v_mul_f32_e32 v0, v116, v0
	v_fma_f32 v0, v116, v0, v116
	v_mul_f32_e32 v0, 0x3f4c422a, v0
	v_add_f32_e32 v0, v0, v0
	v_mul_f32_e32 v0, 0x3fb8aa3b, v0
	v_exp_f32_e32 v0, v0
	v_pk_add_f32 v[124:125], v[58:59], v[124:125]
	v_pk_mul_f32 v[232:233], v[32:33], v[226:227]
	s_mov_b32 s23, 0x62f3000
	v_add_f32_e32 v0, 1.0, v0
	v_rcp_f32_e32 v120, v0
	v_mul_f32_e32 v0, 0x3d372713, v117
	v_mul_f32_e32 v0, v117, v0
	v_fma_f32 v0, v117, v0, v117
	v_mul_f32_e32 v0, 0x3f4c422a, v0
	v_add_f32_e32 v0, v0, v0
	v_mul_f32_e32 v0, 0x3fb8aa3b, v0
	v_exp_f32_e32 v0, v0
	v_pk_mul_f32 v[116:117], v[116:117], 0.5 op_sel_hi:[1,0]
	v_pk_fma_f32 v[232:233], v[16:17], v[106:107], v[232:233]
	v_pk_mul_f32 v[178:179], v[32:33], v[172:173]
	v_add_f32_e32 v0, 1.0, v0
	v_rcp_f32_e32 v121, v0
	v_mul_f32_e32 v0, 0x3d372713, v98
	v_mul_f32_e32 v0, v98, v0
	v_fma_f32 v0, v98, v0, v98
	v_mul_f32_e32 v0, 0x3f4c422a, v0
	v_add_f32_e32 v0, v0, v0
	v_mul_f32_e32 v0, 0x3fb8aa3b, v0
	v_exp_f32_e32 v0, v0
	v_pk_fma_f32 v[120:121], v[120:121], 2.0, 1.0 op_sel_hi:[1,0,0] neg_lo:[1,0,0] neg_hi:[1,0,0]
	s_mov_b64 s[24:25], 0x16000
	v_pk_add_f32 v[120:121], v[120:121], 1.0 op_sel_hi:[1,0]
	v_add_f32_e32 v0, 1.0, v0
	v_rcp_f32_e32 v102, v0
	v_mul_f32_e32 v0, 0x3d372713, v99
	v_mul_f32_e32 v0, v99, v0
	v_fma_f32 v0, v99, v0, v99
	v_mul_f32_e32 v0, 0x3f4c422a, v0
	v_add_f32_e32 v0, v0, v0
	v_mul_f32_e32 v0, 0x3fb8aa3b, v0
	v_exp_f32_e32 v0, v0
	v_pk_mul_f32 v[116:117], v[116:117], v[120:121]
	v_pk_mul_f32 v[98:99], v[98:99], 0.5 op_sel_hi:[1,0]
	v_pk_mul_f32 v[214:215], v[124:125], v[116:117]
	v_add_f32_e32 v0, 1.0, v0
	v_lshlrev_b32_e32 v124, 16, v103
	v_and_b32_e32 v125, 0xffff0000, v103
	v_rcp_f32_e32 v103, v0
	v_lshlrev_b32_e32 v120, 16, v100
	v_and_b32_e32 v121, 0xffff0000, v100
	v_pk_mul_f32 v[116:117], v[28:29], v[220:221]
	v_pk_fma_f32 v[102:103], v[102:103], 2.0, 1.0 op_sel_hi:[1,0,0] neg_lo:[1,0,0] neg_hi:[1,0,0]
	v_pk_fma_f32 v[116:117], v[12:13], v[168:169], v[116:117]
	v_pk_add_f32 v[102:103], v[102:103], 1.0 op_sel_hi:[1,0]
	v_pk_fma_f32 v[116:117], v[44:45], v[124:125], v[116:117]
	v_pk_mul_f32 v[98:99], v[98:99], v[102:103]
	v_pk_mul_f32 v[102:103], v[22:23], v[228:229]
	v_pk_add_f32 v[116:117], v[60:61], v[116:117]
	v_pk_fma_f32 v[102:103], v[6:7], v[122:123], v[102:103]
	v_pk_mul_f32 v[98:99], v[116:117], v[98:99]
	v_pk_fma_f32 v[102:103], v[38:39], v[120:121], v[102:103]
	v_lshlrev_b32_e32 v116, 16, v104
	v_pk_add_f32 v[102:103], v[54:55], v[102:103]
	v_and_b32_e32 v117, 0xffff0000, v104
	v_mul_f32_e32 v0, 0x3d372713, v102
	v_mul_f32_e32 v0, v102, v0
	v_fma_f32 v0, v102, v0, v102
	v_mul_f32_e32 v0, 0x3f4c422a, v0
	v_add_f32_e32 v0, v0, v0
	v_mul_f32_e32 v0, 0x3fb8aa3b, v0
	v_exp_f32_e32 v0, v0
	v_pk_fma_f32 v[218:219], v[46:47], v[116:117], v[218:219]
	v_lshlrev_b32_e32 v100, 16, v105
	v_pk_add_f32 v[218:219], v[62:63], v[218:219]
	v_add_f32_e32 v0, 1.0, v0
	v_rcp_f32_e32 v216, v0
	v_mul_f32_e32 v0, 0x3d372713, v103
	v_mul_f32_e32 v0, v103, v0
	v_fma_f32 v0, v103, v0, v103
	v_mul_f32_e32 v0, 0x3f4c422a, v0
	v_add_f32_e32 v0, v0, v0
	v_mul_f32_e32 v0, 0x3fb8aa3b, v0
	v_exp_f32_e32 v0, v0
	v_pk_mul_f32 v[102:103], v[102:103], 0.5 op_sel_hi:[1,0]
	v_cvt_pk_bf16_f32 v214, v214, v215
	v_cvt_pk_bf16_f32 v215, v98, v99
	v_add_f32_e32 v0, 1.0, v0
	v_rcp_f32_e32 v217, v0
	v_add_co_u32_e32 v98, vcc, s23, v176
	s_mov_b32 s23, 0x62f5000
	v_pk_fma_f32 v[216:217], v[216:217], 2.0, 1.0 op_sel_hi:[1,0,0] neg_lo:[1,0,0] neg_hi:[1,0,0]
	v_addc_co_u32_e32 v99, vcc, 0, v177, vcc
	v_pk_add_f32 v[216:217], v[216:217], 1.0 op_sel_hi:[1,0]
	s_add_i32 s22, s22, -1
	v_pk_mul_f32 v[102:103], v[102:103], v[216:217]
	v_lshl_add_u64 v[160:161], v[160:161], 0, s[24:25]
	v_pk_mul_f32 v[216:217], v[218:219], v[102:103]
	v_lshlrev_b32_e32 v102, 16, v101
	v_and_b32_e32 v103, 0xffff0000, v101
	v_and_b32_e32 v101, 0xffff0000, v105
	v_pk_mul_f32 v[104:105], v[24:25], v[230:231]
	v_pk_fma_f32 v[232:233], v[48:49], v[100:101], v[232:233]
	v_pk_fma_f32 v[104:105], v[8:9], v[110:111], v[104:105]
	v_pk_add_f32 v[232:233], v[64:65], v[232:233]
	v_pk_fma_f32 v[104:105], v[40:41], v[102:103], v[104:105]
	v_cvt_pk_bf16_f32 v216, v216, v217
	v_pk_add_f32 v[104:105], v[56:57], v[104:105]
	s_mov_b64 s[24:25], 0x2c000
	v_mul_f32_e32 v0, 0x3d372713, v104
	v_mul_f32_e32 v0, v104, v0
	v_fma_f32 v0, v104, v0, v104
	v_mul_f32_e32 v0, 0x3f4c422a, v0
	v_add_f32_e32 v0, v0, v0
	v_mul_f32_e32 v0, 0x3fb8aa3b, v0
	v_exp_f32_e32 v0, v0
	v_lshl_add_u64 v[162:163], v[162:163], 0, s[24:25]
	s_cmp_eq_u32 s22, 0
	v_add_f32_e32 v0, 1.0, v0
	v_rcp_f32_e32 v218, v0
	v_mul_f32_e32 v0, 0x3d372713, v105
	v_mul_f32_e32 v0, v105, v0
	v_fma_f32 v0, v105, v0, v105
	v_mul_f32_e32 v0, 0x3f4c422a, v0
	v_add_f32_e32 v0, v0, v0
	v_mul_f32_e32 v0, 0x3fb8aa3b, v0
	v_exp_f32_e32 v0, v0
	v_pk_mul_f32 v[104:105], v[104:105], 0.5 op_sel_hi:[1,0]
	v_add_f32_e32 v0, 1.0, v0
	v_rcp_f32_e32 v219, v0
	s_nop 0
	v_pk_fma_f32 v[218:219], v[218:219], 2.0, 1.0 op_sel_hi:[1,0,0] neg_lo:[1,0,0] neg_hi:[1,0,0]
	s_nop 0
	v_pk_add_f32 v[218:219], v[218:219], 1.0 op_sel_hi:[1,0]
	s_nop 0
	v_pk_mul_f32 v[104:105], v[104:105], v[218:219]
	v_lshlrev_b32_e32 v218, 16, v90
	v_pk_mul_f32 v[104:105], v[232:233], v[104:105]
	v_and_b32_e32 v219, 0xffff0000, v90
	v_cvt_pk_bf16_f32 v217, v104, v105
	global_store_dwordx4 v[98:99], v[214:217], off
	v_pk_mul_f32 v[98:99], v[18:19], v[210:211]
	s_nop 0
	v_pk_fma_f32 v[98:99], v[2:3], v[212:213], v[98:99]
; DI unsigned pack2(float lo, float hi) { f32x2 v = {lo, hi}; bf2_t b = __builtin_convertvector(v, bf2_t); return __builtin_bit_cast(unsigned, b); }
; DI void unpack8(const u32x4& v, float* f) { f[0] = bflo(v.x); f[1] = bfhi(v.x); f[2] = bflo(v.y); f[3] = bfhi(v.y); f[4] = bflo(v.z); f[5] = bfhi(v.z); f[6] = bflo(v.w); f[7] = bfhi(v.w); }
; DI float gelu_tanh(float x) { const float y = 0.7978845608028654f * (x + 0.044715f * x * x * x); const float t = 1.f - 2.f * __builtin_amdgcn_rcpf(1.f + __expf(2.f * y)); return 0.5f * x * (1.f + t); }
; DI void ffn_act_phase(const Params& P, int l) {
;     ...
;       for (int i = 0; i < 8; ++i) {
;         float g0[8], u0[8]; unpack8(G[i], g0); unpack8(U[i], u0);
;         float o[8];
; #pragma unroll
;         for (int e = 0; e < 8; ++e) { const float yg = wg[0][e] * g2[e] + wg[1][e] * g1[e] + wg[2][e] * g0[e] + bg[e]; const float yu = wu[0][e] * u2[e] + wu[1][e] * u1[e] + wu[2][e] * u0[e] + bu[e];
;           o[e] = gelu_tanh(yg) * yu; g2[e] = g1[e]; g1[e] = g0[e]; u2[e] = u1[e]; u1[e] = u0[e]; }
;         u32x4 pk = {pack2(o[0], o[1]), pack2(o[2], o[3]), pack2(o[4], o[5]), pack2(o[6], o[7])};
;         *(u32x4*)(act + (size_t)(r0 + rb * 8 + i) * DFF + ch) = pk;
	v_lshlrev_b32_e32 v214, 16, v91
	v_pk_fma_f32 v[98:99], v[34:35], v[218:219], v[98:99]
	v_and_b32_e32 v215, 0xffff0000, v91
	v_pk_add_f32 v[98:99], v[50:51], v[98:99]
	v_pk_mul_f32 v[90:91], v[20:21], v[128:129]
	v_mul_f32_e32 v0, 0x3d372713, v98
	v_mul_f32_e32 v0, v98, v0
	v_fma_f32 v0, v98, v0, v98
	v_mul_f32_e32 v0, 0x3f4c422a, v0
	v_add_f32_e32 v0, v0, v0
	v_mul_f32_e32 v0, 0x3fb8aa3b, v0
	v_exp_f32_e32 v0, v0
	v_pk_fma_f32 v[90:91], v[4:5], v[224:225], v[90:91]
	v_lshlrev_b32_e32 v216, 16, v94
	v_pk_fma_f32 v[90:91], v[36:37], v[214:215], v[90:91]
	v_add_f32_e32 v0, 1.0, v0
	v_rcp_f32_e32 v104, v0
	v_mul_f32_e32 v0, 0x3d372713, v99
	v_mul_f32_e32 v0, v99, v0
	v_fma_f32 v0, v99, v0, v99
	v_mul_f32_e32 v0, 0x3f4c422a, v0
	v_add_f32_e32 v0, v0, v0
	v_mul_f32_e32 v0, 0x3fb8aa3b, v0
	v_exp_f32_e32 v0, v0
	v_pk_add_f32 v[90:91], v[52:53], v[90:91]
	v_and_b32_e32 v217, 0xffff0000, v94
	v_pk_mul_f32 v[212:213], v[26:27], v[204:205]
	v_add_f32_e32 v0, 1.0, v0
	v_rcp_f32_e32 v105, v0
	v_mul_f32_e32 v0, 0x3d372713, v90
	v_mul_f32_e32 v0, v90, v0
	v_fma_f32 v0, v90, v0, v90
	v_mul_f32_e32 v0, 0x3f4c422a, v0
	v_add_f32_e32 v0, v0, v0
	v_mul_f32_e32 v0, 0x3fb8aa3b, v0
	v_exp_f32_e32 v0, v0
	v_pk_fma_f32 v[202:203], v[10:11], v[202:203], v[212:213]
	v_pk_fma_f32 v[104:105], v[104:105], 2.0, 1.0 op_sel_hi:[1,0,0] neg_lo:[1,0,0] neg_hi:[1,0,0]
	v_lshlrev_b32_e32 v212, 16, v95
	v_add_f32_e32 v0, 1.0, v0
	v_rcp_f32_e32 v94, v0
	v_mul_f32_e32 v0, 0x3d372713, v91
	v_mul_f32_e32 v0, v91, v0
	v_fma_f32 v0, v91, v0, v91
	v_mul_f32_e32 v0, 0x3f4c422a, v0
	v_add_f32_e32 v0, v0, v0
	v_mul_f32_e32 v0, 0x3fb8aa3b, v0
	v_exp_f32_e32 v0, v0
	v_and_b32_e32 v213, 0xffff0000, v95
	v_pk_fma_f32 v[202:203], v[42:43], v[216:217], v[202:203]
	v_pk_mul_f32 v[98:99], v[98:99], 0.5 op_sel_hi:[1,0]
	v_add_f32_e32 v0, 1.0, v0
	v_rcp_f32_e32 v95, v0
	v_pk_add_f32 v[104:105], v[104:105], 1.0 op_sel_hi:[1,0]
	v_pk_add_f32 v[202:203], v[58:59], v[202:203]
	v_pk_mul_f32 v[98:99], v[98:99], v[104:105]
	v_pk_fma_f32 v[94:95], v[94:95], 2.0, 1.0 op_sel_hi:[1,0,0] neg_lo:[1,0,0] neg_hi:[1,0,0]
	v_pk_mul_f32 v[232:233], v[202:203], v[98:99]
	v_pk_mul_f32 v[98:99], v[28:29], v[124:125]
	v_pk_mul_f32 v[90:91], v[90:91], 0.5 op_sel_hi:[1,0]
	v_pk_fma_f32 v[98:99], v[12:13], v[220:221], v[98:99]
	v_pk_add_f32 v[94:95], v[94:95], 1.0 op_sel_hi:[1,0]
	v_pk_fma_f32 v[98:99], v[44:45], v[212:213], v[98:99]
	v_pk_mul_f32 v[90:91], v[90:91], v[94:95]
	v_pk_add_f32 v[98:99], v[60:61], v[98:99]
	v_lshlrev_b32_e32 v202, 16, v92
	v_pk_mul_f32 v[220:221], v[98:99], v[90:91]
	v_pk_mul_f32 v[90:91], v[22:23], v[120:121]
	v_and_b32_e32 v203, 0xffff0000, v92
	v_pk_fma_f32 v[90:91], v[6:7], v[228:229], v[90:91]
	v_pk_mul_f32 v[98:99], v[30:31], v[116:117]
	v_pk_fma_f32 v[90:91], v[38:39], v[202:203], v[90:91]
	v_lshlrev_b32_e32 v104, 16, v96
	v_pk_add_f32 v[90:91], v[54:55], v[90:91]
	v_and_b32_e32 v105, 0xffff0000, v96
	v_mul_f32_e32 v0, 0x3d372713, v90
	v_mul_f32_e32 v0, v90, v0
	v_fma_f32 v0, v90, v0, v90
	v_mul_f32_e32 v0, 0x3f4c422a, v0
	v_add_f32_e32 v0, v0, v0
	v_mul_f32_e32 v0, 0x3fb8aa3b, v0
	v_exp_f32_e32 v0, v0
	v_pk_fma_f32 v[98:99], v[14:15], v[222:223], v[98:99]
	v_add_f32_e32 v0, 1.0, v0
	v_rcp_f32_e32 v94, v0
	v_mul_f32_e32 v0, 0x3d372713, v91
	v_mul_f32_e32 v0, v91, v0
	v_fma_f32 v0, v91, v0, v91
	v_mul_f32_e32 v0, 0x3f4c422a, v0
	v_add_f32_e32 v0, v0, v0
	v_mul_f32_e32 v0, 0x3fb8aa3b, v0
	v_exp_f32_e32 v0, v0
	v_pk_fma_f32 v[98:99], v[46:47], v[104:105], v[98:99]
	v_pk_mul_f32 v[90:91], v[90:91], 0.5 op_sel_hi:[1,0]
	v_pk_add_f32 v[98:99], v[62:63], v[98:99]
	v_add_f32_e32 v0, 1.0, v0
	v_rcp_f32_e32 v95, v0
	s_nop 0
	v_pk_fma_f32 v[94:95], v[94:95], 2.0, 1.0 op_sel_hi:[1,0,0] neg_lo:[1,0,0] neg_hi:[1,0,0]
	s_nop 0
	v_pk_add_f32 v[94:95], v[94:95], 1.0 op_sel_hi:[1,0]
	s_nop 0
	v_pk_mul_f32 v[90:91], v[90:91], v[94:95]
	v_lshlrev_b32_e32 v94, 16, v97
	v_pk_mul_f32 v[222:223], v[98:99], v[90:91]
	v_pk_mul_f32 v[90:91], v[24:25], v[102:103]
	v_lshlrev_b32_e32 v98, 16, v93
	v_and_b32_e32 v99, 0xffff0000, v93
	v_pk_fma_f32 v[90:91], v[8:9], v[230:231], v[90:91]
	v_and_b32_e32 v95, 0xffff0000, v97
	v_pk_fma_f32 v[90:91], v[40:41], v[98:99], v[90:91]
	v_pk_mul_f32 v[96:97], v[32:33], v[100:101]
	v_pk_add_f32 v[90:91], v[56:57], v[90:91]
	v_pk_fma_f32 v[96:97], v[16:17], v[226:227], v[96:97]
	v_mul_f32_e32 v0, 0x3d372713, v90
	v_mul_f32_e32 v0, v90, v0
	v_fma_f32 v0, v90, v0, v90
	v_mul_f32_e32 v0, 0x3f4c422a, v0
	v_add_f32_e32 v0, v0, v0
	v_mul_f32_e32 v0, 0x3fb8aa3b, v0
	v_exp_f32_e32 v0, v0
	v_pk_fma_f32 v[96:97], v[48:49], v[94:95], v[96:97]
	v_add_f32_e32 v0, 1.0, v0
	v_rcp_f32_e32 v92, v0
	v_mul_f32_e32 v0, 0x3d372713, v91
	v_mul_f32_e32 v0, v91, v0
	v_fma_f32 v0, v91, v0, v91
	v_mul_f32_e32 v0, 0x3f4c422a, v0
	v_add_f32_e32 v0, v0, v0
	v_mul_f32_e32 v0, 0x3fb8aa3b, v0
	v_exp_f32_e32 v0, v0
	v_pk_mul_f32 v[90:91], v[90:91], 0.5 op_sel_hi:[1,0]
	v_pk_add_f32 v[96:97], v[64:65], v[96:97]
	v_add_f32_e32 v0, 1.0, v0
	v_rcp_f32_e32 v93, v0
	s_nop 0
	v_pk_fma_f32 v[92:93], v[92:93], 2.0, 1.0 op_sel_hi:[1,0,0] neg_lo:[1,0,0] neg_hi:[1,0,0]
	s_nop 0
	v_pk_add_f32 v[92:93], v[92:93], 1.0 op_sel_hi:[1,0]
	s_nop 0
	v_pk_mul_f32 v[90:91], v[90:91], v[92:93]
	v_cvt_pk_bf16_f32 v92, v222, v223
	v_pk_mul_f32 v[96:97], v[96:97], v[90:91]
	v_cvt_pk_bf16_f32 v90, v232, v233
	v_cvt_pk_bf16_f32 v93, v96, v97
	v_add_co_u32_e32 v96, vcc, s23, v176
	v_cvt_pk_bf16_f32 v91, v220, v221
	s_nop 0
	v_addc_co_u32_e32 v97, vcc, 0, v177, vcc
	global_store_dwordx4 v[96:97], v[90:93], off offset:3072
	v_lshlrev_b32_e32 v96, 16, v82
	v_and_b32_e32 v97, 0xffff0000, v82
	v_pk_fma_f32 v[90:91], v[18:19], v[156:157], v[200:201]
; DI unsigned pack2(float lo, float hi) { f32x2 v = {lo, hi}; bf2_t b = __builtin_convertvector(v, bf2_t); return __builtin_bit_cast(unsigned, b); }
; DI void unpack8(const u32x4& v, float* f) { f[0] = bflo(v.x); f[1] = bfhi(v.x); f[2] = bflo(v.y); f[3] = bfhi(v.y); f[4] = bflo(v.z); f[5] = bfhi(v.z); f[6] = bflo(v.w); f[7] = bfhi(v.w); }
; DI float gelu_tanh(float x) { const float y = 0.7978845608028654f * (x + 0.044715f * x * x * x); const float t = 1.f - 2.f * __builtin_amdgcn_rcpf(1.f + __expf(2.f * y)); return 0.5f * x * (1.f + t); }
; DI void ffn_act_phase(const Params& P, int l) {
;     ...
;       for (int i = 0; i < 8; ++i) {
;         float g0[8], u0[8]; unpack8(G[i], g0); unpack8(U[i], u0);
;         float o[8];
; #pragma unroll
;         for (int e = 0; e < 8; ++e) { const float yg = wg[0][e] * g2[e] + wg[1][e] * g1[e] + wg[2][e] * g0[e] + bg[e]; const float yu = wu[0][e] * u2[e] + wu[1][e] * u1[e] + wu[2][e] * u0[e] + bu[e];
;           o[e] = gelu_tanh(yg) * yu; g2[e] = g1[e]; g1[e] = g0[e]; u2[e] = u1[e]; u1[e] = u0[e]; }
;         u32x4 pk = {pack2(o[0], o[1]), pack2(o[2], o[3]), pack2(o[4], o[5]), pack2(o[6], o[7])};
;         *(u32x4*)(act + (size_t)(r0 + rb * 8 + i) * DFF + ch) = pk;
	v_pk_mul_f32 v[200:201], v[26:27], v[140:141]
	v_pk_fma_f32 v[90:91], v[34:35], v[96:97], v[90:91]
	v_lshlrev_b32_e32 v92, 16, v86
	v_pk_add_f32 v[90:91], v[50:51], v[90:91]
	v_and_b32_e32 v93, 0xffff0000, v86
	v_mul_f32_e32 v0, 0x3d372713, v90
	v_mul_f32_e32 v0, v90, v0
	v_fma_f32 v0, v90, v0, v90
	v_mul_f32_e32 v0, 0x3f4c422a, v0
	v_add_f32_e32 v0, v0, v0
	v_mul_f32_e32 v0, 0x3fb8aa3b, v0
	v_exp_f32_e32 v0, v0
	v_pk_fma_f32 v[146:147], v[10:11], v[146:147], v[200:201]
	s_mov_b32 s23, 0x62ea000
	v_pk_fma_f32 v[146:147], v[42:43], v[92:93], v[146:147]
	v_add_f32_e32 v0, 1.0, v0
	v_rcp_f32_e32 v158, v0
	v_mul_f32_e32 v0, 0x3d372713, v91
	v_mul_f32_e32 v0, v91, v0
	v_fma_f32 v0, v91, v0, v91
	v_mul_f32_e32 v0, 0x3f4c422a, v0
	v_add_f32_e32 v0, v0, v0
	v_mul_f32_e32 v0, 0x3fb8aa3b, v0
	v_exp_f32_e32 v0, v0
	v_pk_mul_f32 v[90:91], v[90:91], 0.5 op_sel_hi:[1,0]
	v_pk_add_f32 v[146:147], v[58:59], v[146:147]
	v_add_f32_e32 v0, 1.0, v0
	v_rcp_f32_e32 v159, v0
	s_nop 0
	v_pk_fma_f32 v[158:159], v[158:159], 2.0, 1.0 op_sel_hi:[1,0,0] neg_lo:[1,0,0] neg_hi:[1,0,0]
	s_nop 0
	v_pk_add_f32 v[158:159], v[158:159], 1.0 op_sel_hi:[1,0]
	s_nop 0
	v_pk_mul_f32 v[90:91], v[90:91], v[158:159]
	v_pk_mul_f32 v[158:159], v[26:27], v[92:93]
	v_pk_mul_f32 v[90:91], v[146:147], v[90:91]
	v_pk_mul_f32 v[146:147], v[18:19], v[96:97]
	v_pk_fma_f32 v[140:141], v[10:11], v[140:141], v[158:159]
	v_pk_fma_f32 v[146:147], v[2:3], v[156:157], v[146:147]
	v_pk_fma_f32 v[140:141], v[42:43], v[198:199], v[140:141]
	v_pk_fma_f32 v[146:147], v[34:35], v[194:195], v[146:147]
	v_pk_add_f32 v[140:141], v[58:59], v[140:141]
	v_pk_add_f32 v[146:147], v[50:51], v[146:147]
	s_waitcnt vmcnt(0) lgkmcnt(0)
	v_and_b32_e32 v159, 0xffff0000, v70
	v_mul_f32_e32 v0, 0x3d372713, v146
	v_mul_f32_e32 v0, v146, v0
	v_fma_f32 v0, v146, v0, v146
	v_mul_f32_e32 v0, 0x3f4c422a, v0
	v_add_f32_e32 v0, v0, v0
	v_mul_f32_e32 v0, 0x3fb8aa3b, v0
	v_exp_f32_e32 v0, v0
	v_cvt_pk_bf16_f32 v90, v90, v91
	v_add_f32_e32 v0, 1.0, v0
	v_rcp_f32_e32 v156, v0
	v_mul_f32_e32 v0, 0x3d372713, v147
	v_mul_f32_e32 v0, v147, v0
	v_fma_f32 v0, v147, v0, v147
	v_mul_f32_e32 v0, 0x3f4c422a, v0
	v_add_f32_e32 v0, v0, v0
	v_mul_f32_e32 v0, 0x3fb8aa3b, v0
	v_exp_f32_e32 v0, v0
	v_pk_mul_f32 v[146:147], v[146:147], 0.5 op_sel_hi:[1,0]
	v_add_f32_e32 v0, 1.0, v0
	v_rcp_f32_e32 v157, v0
	s_nop 0
	v_pk_fma_f32 v[156:157], v[156:157], 2.0, 1.0 op_sel_hi:[1,0,0] neg_lo:[1,0,0] neg_hi:[1,0,0]
	s_nop 0
	v_pk_add_f32 v[156:157], v[156:157], 1.0 op_sel_hi:[1,0]
	s_nop 0
	v_pk_mul_f32 v[146:147], v[146:147], v[156:157]
	v_and_b32_e32 v157, 0xffff0000, v66
	v_pk_mul_f32 v[140:141], v[140:141], v[146:147]
	v_pk_mul_f32 v[146:147], v[26:27], v[198:199]
	v_cvt_pk_bf16_f32 v86, v140, v141
	v_pk_mul_f32 v[140:141], v[18:19], v[194:195]
	v_pk_fma_f32 v[92:93], v[10:11], v[92:93], v[146:147]
	v_pk_fma_f32 v[96:97], v[2:3], v[96:97], v[140:141]
	v_pk_fma_f32 v[92:93], v[42:43], v[166:167], v[92:93]
	v_pk_fma_f32 v[96:97], v[34:35], v[196:197], v[96:97]
	v_pk_add_f32 v[92:93], v[58:59], v[92:93]
	v_pk_add_f32 v[96:97], v[50:51], v[96:97]
	v_lshlrev_b32_e32 v166, 16, v74
	v_mul_f32_e32 v0, 0x3d372713, v96
	v_mul_f32_e32 v0, v96, v0
	v_fma_f32 v0, v96, v0, v96
	v_mul_f32_e32 v0, 0x3f4c422a, v0
	v_add_f32_e32 v0, v0, v0
	v_mul_f32_e32 v0, 0x3fb8aa3b, v0
	v_exp_f32_e32 v0, v0
	v_and_b32_e32 v167, 0xffff0000, v74
	v_lshlrev_b32_e32 v146, 16, v78
	v_and_b32_e32 v147, 0xffff0000, v78
	v_add_f32_e32 v0, 1.0, v0
	v_rcp_f32_e32 v140, v0
	v_mul_f32_e32 v0, 0x3d372713, v97
	v_mul_f32_e32 v0, v97, v0
	v_fma_f32 v0, v97, v0, v97
	v_mul_f32_e32 v0, 0x3f4c422a, v0
	v_add_f32_e32 v0, v0, v0
	v_mul_f32_e32 v0, 0x3fb8aa3b, v0
	v_exp_f32_e32 v0, v0
	v_pk_mul_f32 v[96:97], v[96:97], 0.5 op_sel_hi:[1,0]
	v_pk_mul_f32 v[194:195], v[26:27], v[146:147]
	v_add_f32_e32 v0, 1.0, v0
	v_rcp_f32_e32 v141, v0
	v_pk_fma_f32 v[194:195], v[10:11], v[216:217], v[194:195]
	v_pk_fma_f32 v[140:141], v[140:141], 2.0, 1.0 op_sel_hi:[1,0,0] neg_lo:[1,0,0] neg_hi:[1,0,0]
	s_nop 0
	v_pk_add_f32 v[140:141], v[140:141], 1.0 op_sel_hi:[1,0]
	s_nop 0
	v_pk_mul_f32 v[96:97], v[96:97], v[140:141]
	s_nop 0
	v_pk_mul_f32 v[92:93], v[92:93], v[96:97]
	v_pk_mul_f32 v[96:97], v[26:27], v[216:217]
	v_cvt_pk_bf16_f32 v82, v92, v93
	v_pk_mul_f32 v[92:93], v[18:19], v[218:219]
	v_pk_fma_f32 v[96:97], v[10:11], v[204:205], v[96:97]
	v_pk_fma_f32 v[92:93], v[2:3], v[210:211], v[92:93]
	v_pk_fma_f32 v[96:97], v[42:43], v[146:147], v[96:97]
	v_pk_fma_f32 v[92:93], v[34:35], v[166:167], v[92:93]
	v_pk_add_f32 v[96:97], v[58:59], v[96:97]
	v_pk_add_f32 v[92:93], v[50:51], v[92:93]
	s_nop 0
	v_mul_f32_e32 v0, 0x3d372713, v92
	v_mul_f32_e32 v0, v92, v0
	v_fma_f32 v0, v92, v0, v92
	v_mul_f32_e32 v0, 0x3f4c422a, v0
	v_add_f32_e32 v0, v0, v0
	v_mul_f32_e32 v0, 0x3fb8aa3b, v0
	v_exp_f32_e32 v0, v0
	s_nop 0
	v_add_f32_e32 v0, 1.0, v0
	v_rcp_f32_e32 v140, v0
	v_mul_f32_e32 v0, 0x3d372713, v93
	v_mul_f32_e32 v0, v93, v0
	v_fma_f32 v0, v93, v0, v93
	v_mul_f32_e32 v0, 0x3f4c422a, v0
	v_add_f32_e32 v0, v0, v0
	v_mul_f32_e32 v0, 0x3fb8aa3b, v0
	v_exp_f32_e32 v0, v0
	v_pk_mul_f32 v[92:93], v[92:93], 0.5 op_sel_hi:[1,0]
	v_add_f32_e32 v0, 1.0, v0
	v_rcp_f32_e32 v141, v0
	s_nop 0
	v_pk_fma_f32 v[140:141], v[140:141], 2.0, 1.0 op_sel_hi:[1,0,0] neg_lo:[1,0,0] neg_hi:[1,0,0]
	s_nop 0
	v_pk_add_f32 v[140:141], v[140:141], 1.0 op_sel_hi:[1,0]
	s_nop 0
	v_pk_mul_f32 v[92:93], v[92:93], v[140:141]
	v_lshlrev_b32_e32 v141, 16, v66
	v_pk_mul_f32 v[92:93], v[96:97], v[92:93]
	v_mov_b32_e32 v156, v141
	v_cvt_pk_bf16_f32 v74, v92, v93
	v_pk_mul_f32 v[92:93], v[18:19], v[166:167]
	v_lshlrev_b32_e32 v140, 16, v70
; DI unsigned pack2(float lo, float hi) { f32x2 v = {lo, hi}; bf2_t b = __builtin_convertvector(v, bf2_t); return __builtin_bit_cast(unsigned, b); }
; DI void unpack8(const u32x4& v, float* f) { f[0] = bflo(v.x); f[1] = bfhi(v.x); f[2] = bflo(v.y); f[3] = bfhi(v.y); f[4] = bflo(v.z); f[5] = bfhi(v.z); f[6] = bflo(v.w); f[7] = bfhi(v.w); }
; DI float gelu_tanh(float x) { const float y = 0.7978845608028654f * (x + 0.044715f * x * x * x); const float t = 1.f - 2.f * __builtin_amdgcn_rcpf(1.f + __expf(2.f * y)); return 0.5f * x * (1.f + t); }
; DI void ffn_act_phase(const Params& P, int l) {
;     ...
;       for (int i = 0; i < 8; ++i) {
;         float g0[8], u0[8]; unpack8(G[i], g0); unpack8(U[i], u0);
;         float o[8];
; #pragma unroll
;         for (int e = 0; e < 8; ++e) { const float yg = wg[0][e] * g2[e] + wg[1][e] * g1[e] + wg[2][e] * g0[e] + bg[e]; const float yu = wu[0][e] * u2[e] + wu[1][e] * u1[e] + wu[2][e] * u0[e] + bu[e];
;           o[e] = gelu_tanh(yg) * yu; g2[e] = g1[e]; g1[e] = g0[e]; u2[e] = u1[e]; u1[e] = u0[e]; }
;         u32x4 pk = {pack2(o[0], o[1]), pack2(o[2], o[3]), pack2(o[4], o[5]), pack2(o[6], o[7])};
;         *(u32x4*)(act + (size_t)(r0 + rb * 8 + i) * DFF + ch) = pk;
	v_pk_fma_f32 v[92:93], v[2:3], v[218:219], v[92:93]
	v_mov_b32_e32 v158, v140
	v_pk_fma_f32 v[92:93], v[34:35], v[156:157], v[92:93]
	v_pk_fma_f32 v[194:195], v[42:43], v[158:159], v[194:195]
	v_pk_add_f32 v[92:93], v[50:51], v[92:93]
	v_pk_add_f32 v[194:195], v[58:59], v[194:195]
	v_mul_f32_e32 v0, 0x3d372713, v92
	v_mul_f32_e32 v0, v92, v0
	v_fma_f32 v0, v92, v0, v92
	v_mul_f32_e32 v0, 0x3f4c422a, v0
	v_add_f32_e32 v0, v0, v0
	v_mul_f32_e32 v0, 0x3fb8aa3b, v0
	v_exp_f32_e32 v0, v0
	s_nop 0
	v_add_f32_e32 v0, 1.0, v0
	v_rcp_f32_e32 v96, v0
	v_mul_f32_e32 v0, 0x3d372713, v93
	v_mul_f32_e32 v0, v93, v0
	v_fma_f32 v0, v93, v0, v93
	v_mul_f32_e32 v0, 0x3f4c422a, v0
	v_add_f32_e32 v0, v0, v0
	v_mul_f32_e32 v0, 0x3fb8aa3b, v0
	v_exp_f32_e32 v0, v0
	v_pk_mul_f32 v[92:93], v[92:93], 0.5 op_sel_hi:[1,0]
	v_add_f32_e32 v0, 1.0, v0
	v_rcp_f32_e32 v97, v0
	s_nop 0
	v_pk_fma_f32 v[96:97], v[96:97], 2.0, 1.0 op_sel_hi:[1,0,0] neg_lo:[1,0,0] neg_hi:[1,0,0]
	s_nop 0
	v_pk_add_f32 v[96:97], v[96:97], 1.0 op_sel_hi:[1,0]
	s_nop 0
	v_pk_mul_f32 v[92:93], v[92:93], v[96:97]
	s_nop 0
	v_pk_mul_f32 v[96:97], v[194:195], v[92:93]
	v_lshlrev_b32_e32 v92, 16, v83
	v_and_b32_e32 v93, 0xffff0000, v83
	v_pk_fma_f32 v[192:193], v[36:37], v[92:93], v[192:193]
	v_lshlrev_b32_e32 v194, 16, v87
	v_pk_add_f32 v[192:193], v[52:53], v[192:193]
	v_and_b32_e32 v195, 0xffff0000, v87
	v_mul_f32_e32 v0, 0x3d372713, v192
	v_mul_f32_e32 v0, v192, v0
	v_fma_f32 v0, v192, v0, v192
	v_mul_f32_e32 v0, 0x3f4c422a, v0
	v_add_f32_e32 v0, v0, v0
	v_mul_f32_e32 v0, 0x3fb8aa3b, v0
	v_exp_f32_e32 v0, v0
	v_pk_fma_f32 v[144:145], v[44:45], v[194:195], v[144:145]
	v_add_f32_e32 v0, 1.0, v0
	v_rcp_f32_e32 v196, v0
	v_mul_f32_e32 v0, 0x3d372713, v193
	v_mul_f32_e32 v0, v193, v0
	v_fma_f32 v0, v193, v0, v193
	v_mul_f32_e32 v0, 0x3f4c422a, v0
	v_add_f32_e32 v0, v0, v0
	v_mul_f32_e32 v0, 0x3fb8aa3b, v0
	v_exp_f32_e32 v0, v0
	v_pk_mul_f32 v[192:193], v[192:193], 0.5 op_sel_hi:[1,0]
	v_pk_add_f32 v[144:145], v[60:61], v[144:145]
	v_add_f32_e32 v0, 1.0, v0
	v_rcp_f32_e32 v197, v0
	s_nop 0
	v_pk_fma_f32 v[186:187], v[196:197], 2.0, 1.0 op_sel_hi:[1,0,0] neg_lo:[1,0,0] neg_hi:[1,0,0]
	s_nop 0
	v_pk_add_f32 v[186:187], v[186:187], 1.0 op_sel_hi:[1,0]
	s_nop 0
	v_pk_mul_f32 v[186:187], v[192:193], v[186:187]
	s_nop 0
	v_pk_mul_f32 v[144:145], v[144:145], v[186:187]
	v_pk_mul_f32 v[186:187], v[28:29], v[194:195]
	v_cvt_pk_bf16_f32 v91, v144, v145
	v_pk_mul_f32 v[144:145], v[20:21], v[92:93]
	v_pk_fma_f32 v[152:153], v[12:13], v[152:153], v[186:187]
	v_pk_fma_f32 v[144:145], v[4:5], v[148:149], v[144:145]
	v_pk_fma_f32 v[152:153], v[44:45], v[190:191], v[152:153]
	v_pk_fma_f32 v[144:145], v[36:37], v[184:185], v[144:145]
	v_pk_add_f32 v[152:153], v[60:61], v[152:153]
	v_pk_add_f32 v[144:145], v[52:53], v[144:145]
	s_nop 0
	v_mul_f32_e32 v0, 0x3d372713, v144
	v_mul_f32_e32 v0, v144, v0
	v_fma_f32 v0, v144, v0, v144
	v_mul_f32_e32 v0, 0x3f4c422a, v0
	v_add_f32_e32 v0, v0, v0
	v_mul_f32_e32 v0, 0x3fb8aa3b, v0
	v_exp_f32_e32 v0, v0
	s_nop 0
	v_add_f32_e32 v0, 1.0, v0
	v_rcp_f32_e32 v148, v0
	v_mul_f32_e32 v0, 0x3d372713, v145
	v_mul_f32_e32 v0, v145, v0
	v_fma_f32 v0, v145, v0, v145
	v_mul_f32_e32 v0, 0x3f4c422a, v0
	v_add_f32_e32 v0, v0, v0
	v_mul_f32_e32 v0, 0x3fb8aa3b, v0
	v_exp_f32_e32 v0, v0
	v_pk_mul_f32 v[144:145], v[144:145], 0.5 op_sel_hi:[1,0]
	v_add_f32_e32 v0, 1.0, v0
	v_rcp_f32_e32 v149, v0
	s_nop 0
	v_pk_fma_f32 v[148:149], v[148:149], 2.0, 1.0 op_sel_hi:[1,0,0] neg_lo:[1,0,0] neg_hi:[1,0,0]
	s_nop 0
	v_pk_add_f32 v[148:149], v[148:149], 1.0 op_sel_hi:[1,0]
	s_nop 0
	v_pk_mul_f32 v[144:145], v[144:145], v[148:149]
	v_pk_mul_f32 v[148:149], v[28:29], v[190:191]
	v_pk_mul_f32 v[144:145], v[152:153], v[144:145]
	v_pk_fma_f32 v[148:149], v[12:13], v[194:195], v[148:149]
	v_cvt_pk_bf16_f32 v87, v144, v145
	v_pk_mul_f32 v[144:145], v[20:21], v[184:185]
	v_pk_fma_f32 v[148:149], v[44:45], v[168:169], v[148:149]
	v_pk_fma_f32 v[92:93], v[4:5], v[92:93], v[144:145]
	v_lshlrev_b32_e32 v168, 16, v75
	v_pk_fma_f32 v[92:93], v[36:37], v[188:189], v[92:93]
	v_and_b32_e32 v169, 0xffff0000, v75
	v_pk_add_f32 v[92:93], v[52:53], v[92:93]
	v_pk_add_f32 v[148:149], v[60:61], v[148:149]
	v_mul_f32_e32 v0, 0x3d372713, v92
	v_mul_f32_e32 v0, v92, v0
	v_fma_f32 v0, v92, v0, v92
	v_mul_f32_e32 v0, 0x3f4c422a, v0
	v_add_f32_e32 v0, v0, v0
	v_mul_f32_e32 v0, 0x3fb8aa3b, v0
	v_exp_f32_e32 v0, v0
	v_lshlrev_b32_e32 v152, 16, v71
	v_and_b32_e32 v153, 0xffff0000, v71
	v_add_f32_e32 v0, 1.0, v0
	v_rcp_f32_e32 v144, v0
	v_mul_f32_e32 v0, 0x3d372713, v93
	v_mul_f32_e32 v0, v93, v0
	v_fma_f32 v0, v93, v0, v93
	v_mul_f32_e32 v0, 0x3f4c422a, v0
	v_add_f32_e32 v0, v0, v0
	v_mul_f32_e32 v0, 0x3fb8aa3b, v0
	v_exp_f32_e32 v0, v0
	v_pk_mul_f32 v[92:93], v[92:93], 0.5 op_sel_hi:[1,0]
	v_add_f32_e32 v0, 1.0, v0
	v_rcp_f32_e32 v145, v0
	s_nop 0
	v_pk_fma_f32 v[144:145], v[144:145], 2.0, 1.0 op_sel_hi:[1,0,0] neg_lo:[1,0,0] neg_hi:[1,0,0]
	s_nop 0
	v_pk_add_f32 v[144:145], v[144:145], 1.0 op_sel_hi:[1,0]
	s_nop 0
	v_pk_mul_f32 v[92:93], v[92:93], v[144:145]
	v_lshlrev_b32_e32 v144, 16, v79
	v_and_b32_e32 v145, 0xffff0000, v79
	v_pk_mul_f32 v[78:79], v[20:21], v[214:215]
	v_pk_mul_f32 v[92:93], v[148:149], v[92:93]
	v_pk_fma_f32 v[78:79], v[4:5], v[128:129], v[78:79]
	v_cvt_pk_bf16_f32 v83, v92, v93
	v_pk_fma_f32 v[78:79], v[36:37], v[168:169], v[78:79]
	v_pk_mul_f32 v[92:93], v[28:29], v[212:213]
	v_pk_add_f32 v[78:79], v[52:53], v[78:79]
	v_pk_fma_f32 v[92:93], v[12:13], v[124:125], v[92:93]
	v_mul_f32_e32 v0, 0x3d372713, v78
	v_mul_f32_e32 v0, v78, v0
	v_fma_f32 v0, v78, v0, v78
	v_mul_f32_e32 v0, 0x3f4c422a, v0
	v_add_f32_e32 v0, v0, v0
; DI unsigned pack2(float lo, float hi) { f32x2 v = {lo, hi}; bf2_t b = __builtin_convertvector(v, bf2_t); return __builtin_bit_cast(unsigned, b); }
; DI void unpack8(const u32x4& v, float* f) { f[0] = bflo(v.x); f[1] = bfhi(v.x); f[2] = bflo(v.y); f[3] = bfhi(v.y); f[4] = bflo(v.z); f[5] = bfhi(v.z); f[6] = bflo(v.w); f[7] = bfhi(v.w); }
; DI float gelu_tanh(float x) { const float y = 0.7978845608028654f * (x + 0.044715f * x * x * x); const float t = 1.f - 2.f * __builtin_amdgcn_rcpf(1.f + __expf(2.f * y)); return 0.5f * x * (1.f + t); }
; DI void ffn_act_phase(const Params& P, int l) {
;     ...
;       for (int i = 0; i < 8; ++i) {
;         float g0[8], u0[8]; unpack8(G[i], g0); unpack8(U[i], u0);
;         float o[8];
; #pragma unroll
;         for (int e = 0; e < 8; ++e) { const float yg = wg[0][e] * g2[e] + wg[1][e] * g1[e] + wg[2][e] * g0[e] + bg[e]; const float yu = wu[0][e] * u2[e] + wu[1][e] * u1[e] + wu[2][e] * u0[e] + bu[e];
;           o[e] = gelu_tanh(yg) * yu; g2[e] = g1[e]; g1[e] = g0[e]; u2[e] = u1[e]; u1[e] = u0[e]; }
;         u32x4 pk = {pack2(o[0], o[1]), pack2(o[2], o[3]), pack2(o[4], o[5]), pack2(o[6], o[7])};
;         *(u32x4*)(act + (size_t)(r0 + rb * 8 + i) * DFF + ch) = pk;
	v_mul_f32_e32 v0, 0x3fb8aa3b, v0
	v_exp_f32_e32 v0, v0
	v_lshlrev_b32_e32 v148, 16, v67
	v_and_b32_e32 v149, 0xffff0000, v67
	v_pk_mul_f32 v[66:67], v[20:21], v[168:169]
	v_add_f32_e32 v0, 1.0, v0
	v_rcp_f32_e32 v124, v0
	v_mul_f32_e32 v0, 0x3d372713, v79
	v_mul_f32_e32 v0, v79, v0
	v_fma_f32 v0, v79, v0, v79
	v_mul_f32_e32 v0, 0x3f4c422a, v0
	v_add_f32_e32 v0, v0, v0
	v_mul_f32_e32 v0, 0x3fb8aa3b, v0
	v_exp_f32_e32 v0, v0
	v_pk_fma_f32 v[66:67], v[4:5], v[214:215], v[66:67]
	v_pk_fma_f32 v[92:93], v[44:45], v[144:145], v[92:93]
	v_pk_fma_f32 v[66:67], v[36:37], v[148:149], v[66:67]
	v_add_f32_e32 v0, 1.0, v0
	v_pk_add_f32 v[66:67], v[52:53], v[66:67]
	v_rcp_f32_e32 v125, v0
	v_mul_f32_e32 v0, 0x3d372713, v66
	v_mul_f32_e32 v0, v66, v0
	v_fma_f32 v0, v66, v0, v66
	v_mul_f32_e32 v0, 0x3f4c422a, v0
	v_add_f32_e32 v0, v0, v0
	v_mul_f32_e32 v0, 0x3fb8aa3b, v0
	v_exp_f32_e32 v0, v0
	v_pk_fma_f32 v[124:125], v[124:125], 2.0, 1.0 op_sel_hi:[1,0,0] neg_lo:[1,0,0] neg_hi:[1,0,0]
	v_pk_mul_f32 v[78:79], v[78:79], 0.5 op_sel_hi:[1,0]
	v_pk_add_f32 v[124:125], v[124:125], 1.0 op_sel_hi:[1,0]
	v_add_f32_e32 v0, 1.0, v0
	v_rcp_f32_e32 v70, v0
	v_mul_f32_e32 v0, 0x3d372713, v67
	v_mul_f32_e32 v0, v67, v0
	v_fma_f32 v0, v67, v0, v67
	v_mul_f32_e32 v0, 0x3f4c422a, v0
	v_add_f32_e32 v0, v0, v0
	v_mul_f32_e32 v0, 0x3fb8aa3b, v0
	v_exp_f32_e32 v0, v0
	v_pk_add_f32 v[92:93], v[60:61], v[92:93]
	v_pk_mul_f32 v[78:79], v[78:79], v[124:125]
	v_pk_mul_f32 v[66:67], v[66:67], 0.5 op_sel_hi:[1,0]
	v_add_f32_e32 v0, 1.0, v0
	v_rcp_f32_e32 v71, v0
	v_pk_mul_f32 v[78:79], v[92:93], v[78:79]
	v_pk_fma_f32 v[92:93], v[22:23], v[142:143], v[182:183]
	v_cvt_pk_bf16_f32 v75, v78, v79
	v_pk_mul_f32 v[78:79], v[28:29], v[144:145]
	v_pk_fma_f32 v[70:71], v[70:71], 2.0, 1.0 op_sel_hi:[1,0,0] neg_lo:[1,0,0] neg_hi:[1,0,0]
	v_pk_fma_f32 v[78:79], v[12:13], v[212:213], v[78:79]
	v_pk_add_f32 v[70:71], v[70:71], 1.0 op_sel_hi:[1,0]
	v_pk_fma_f32 v[78:79], v[44:45], v[152:153], v[78:79]
	v_pk_mul_f32 v[66:67], v[66:67], v[70:71]
	v_pk_add_f32 v[78:79], v[60:61], v[78:79]
	v_pk_fma_f32 v[128:129], v[14:15], v[150:151], v[174:175]
	v_pk_mul_f32 v[70:71], v[78:79], v[66:67]
	v_lshlrev_b32_e32 v66, 16, v84
	v_and_b32_e32 v67, 0xffff0000, v84
	v_pk_fma_f32 v[92:93], v[38:39], v[66:67], v[92:93]
	v_lshlrev_b32_e32 v78, 16, v88
	v_pk_add_f32 v[92:93], v[54:55], v[92:93]
	v_and_b32_e32 v79, 0xffff0000, v88
	v_mul_f32_e32 v0, 0x3d372713, v92
	v_mul_f32_e32 v0, v92, v0
	v_fma_f32 v0, v92, v0, v92
	v_mul_f32_e32 v0, 0x3f4c422a, v0
	v_add_f32_e32 v0, v0, v0
	v_mul_f32_e32 v0, 0x3fb8aa3b, v0
	v_exp_f32_e32 v0, v0
	v_pk_fma_f32 v[128:129], v[46:47], v[78:79], v[128:129]
	v_lshlrev_b32_e32 v174, 16, v76
	v_pk_add_f32 v[128:129], v[62:63], v[128:129]
	v_add_f32_e32 v0, 1.0, v0
	v_rcp_f32_e32 v124, v0
	v_mul_f32_e32 v0, 0x3d372713, v93
	v_mul_f32_e32 v0, v93, v0
	v_fma_f32 v0, v93, v0, v93
	v_mul_f32_e32 v0, 0x3f4c422a, v0
	v_add_f32_e32 v0, v0, v0
	v_mul_f32_e32 v0, 0x3fb8aa3b, v0
	v_exp_f32_e32 v0, v0
	v_pk_mul_f32 v[92:93], v[92:93], 0.5 op_sel_hi:[1,0]
	v_and_b32_e32 v175, 0xffff0000, v76
	v_lshlrev_b32_e32 v150, 16, v80
	v_add_f32_e32 v0, 1.0, v0
	v_rcp_f32_e32 v125, v0
	v_and_b32_e32 v151, 0xffff0000, v80
	v_pk_fma_f32 v[124:125], v[124:125], 2.0, 1.0 op_sel_hi:[1,0,0] neg_lo:[1,0,0] neg_hi:[1,0,0]
	s_nop 0
	v_pk_add_f32 v[124:125], v[124:125], 1.0 op_sel_hi:[1,0]
	s_nop 0
	v_pk_mul_f32 v[92:93], v[92:93], v[124:125]
	v_pk_mul_f32 v[124:125], v[22:23], v[66:67]
	v_pk_mul_f32 v[92:93], v[128:129], v[92:93]
	v_pk_fma_f32 v[124:125], v[6:7], v[142:143], v[124:125]
	v_pk_mul_f32 v[142:143], v[30:31], v[78:79]
	v_pk_fma_f32 v[124:125], v[38:39], v[118:119], v[124:125]
	v_pk_mul_f32 v[118:119], v[22:23], v[118:119]
	v_pk_add_f32 v[124:125], v[54:55], v[124:125]
	v_pk_fma_f32 v[66:67], v[6:7], v[66:67], v[118:119]
	v_mul_f32_e32 v0, 0x3d372713, v124
	v_mul_f32_e32 v0, v124, v0
	v_fma_f32 v0, v124, v0, v124
	v_mul_f32_e32 v0, 0x3f4c422a, v0
	v_add_f32_e32 v0, v0, v0
	v_mul_f32_e32 v0, 0x3fb8aa3b, v0
	v_exp_f32_e32 v0, v0
	v_pk_fma_f32 v[66:67], v[38:39], v[122:123], v[66:67]
	v_pk_fma_f32 v[142:143], v[14:15], v[154:155], v[142:143]
	v_pk_add_f32 v[66:67], v[54:55], v[66:67]
	v_add_f32_e32 v0, 1.0, v0
	v_rcp_f32_e32 v128, v0
	v_mul_f32_e32 v0, 0x3d372713, v125
	v_mul_f32_e32 v0, v125, v0
	v_fma_f32 v0, v125, v0, v125
	v_mul_f32_e32 v0, 0x3f4c422a, v0
	v_add_f32_e32 v0, v0, v0
	v_mul_f32_e32 v0, 0x3fb8aa3b, v0
	v_exp_f32_e32 v0, v0
	v_pk_fma_f32 v[142:143], v[46:47], v[126:127], v[142:143]
	v_pk_mul_f32 v[124:125], v[124:125], 0.5 op_sel_hi:[1,0]
	v_pk_add_f32 v[142:143], v[62:63], v[142:143]
	v_add_f32_e32 v0, 1.0, v0
	v_rcp_f32_e32 v129, v0
	v_mul_f32_e32 v0, 0x3d372713, v66
	v_mul_f32_e32 v0, v66, v0
	v_fma_f32 v0, v66, v0, v66
	v_mul_f32_e32 v0, 0x3f4c422a, v0
	v_add_f32_e32 v0, v0, v0
	v_mul_f32_e32 v0, 0x3fb8aa3b, v0
	v_exp_f32_e32 v0, v0
	v_pk_fma_f32 v[128:129], v[128:129], 2.0, 1.0 op_sel_hi:[1,0,0] neg_lo:[1,0,0] neg_hi:[1,0,0]
	v_lshlrev_b32_e32 v154, 16, v72
	v_pk_add_f32 v[128:129], v[128:129], 1.0 op_sel_hi:[1,0]
	v_add_f32_e32 v0, 1.0, v0
	v_rcp_f32_e32 v118, v0
	v_mul_f32_e32 v0, 0x3d372713, v67
	v_mul_f32_e32 v0, v67, v0
	v_fma_f32 v0, v67, v0, v67
	v_mul_f32_e32 v0, 0x3f4c422a, v0
	v_add_f32_e32 v0, v0, v0
	v_mul_f32_e32 v0, 0x3fb8aa3b, v0
	v_exp_f32_e32 v0, v0
	v_pk_mul_f32 v[124:125], v[124:125], v[128:129]
	v_pk_mul_f32 v[66:67], v[66:67], 0.5 op_sel_hi:[1,0]
	v_pk_mul_f32 v[124:125], v[142:143], v[124:125]
	v_add_f32_e32 v0, 1.0, v0
	v_rcp_f32_e32 v119, v0
	v_cvt_pk_bf16_f32 v88, v124, v125
	v_pk_mul_f32 v[124:125], v[30:31], v[126:127]
	v_lshlrev_b32_e32 v142, 16, v68
; DI unsigned pack2(float lo, float hi) { f32x2 v = {lo, hi}; bf2_t b = __builtin_convertvector(v, bf2_t); return __builtin_bit_cast(unsigned, b); }
; DI void unpack8(const u32x4& v, float* f) { f[0] = bflo(v.x); f[1] = bfhi(v.x); f[2] = bflo(v.y); f[3] = bfhi(v.y); f[4] = bflo(v.z); f[5] = bfhi(v.z); f[6] = bflo(v.w); f[7] = bfhi(v.w); }
; DI float gelu_tanh(float x) { const float y = 0.7978845608028654f * (x + 0.044715f * x * x * x); const float t = 1.f - 2.f * __builtin_amdgcn_rcpf(1.f + __expf(2.f * y)); return 0.5f * x * (1.f + t); }
; DI void ffn_act_phase(const Params& P, int l) {
;     ...
;       for (int i = 0; i < 8; ++i) {
;         float g0[8], u0[8]; unpack8(G[i], g0); unpack8(U[i], u0);
;         float o[8];
; #pragma unroll
;         for (int e = 0; e < 8; ++e) { const float yg = wg[0][e] * g2[e] + wg[1][e] * g1[e] + wg[2][e] * g0[e] + bg[e]; const float yu = wu[0][e] * u2[e] + wu[1][e] * u1[e] + wu[2][e] * u0[e] + bu[e];
;           o[e] = gelu_tanh(yg) * yu; g2[e] = g1[e]; g1[e] = g0[e]; u2[e] = u1[e]; u1[e] = u0[e]; }
;         u32x4 pk = {pack2(o[0], o[1]), pack2(o[2], o[3]), pack2(o[4], o[5]), pack2(o[6], o[7])};
;         *(u32x4*)(act + (size_t)(r0 + rb * 8 + i) * DFF + ch) = pk;
	v_pk_fma_f32 v[78:79], v[14:15], v[78:79], v[124:125]
	v_and_b32_e32 v143, 0xffff0000, v68
	v_pk_fma_f32 v[78:79], v[46:47], v[114:115], v[78:79]
	v_pk_fma_f32 v[114:115], v[118:119], 2.0, 1.0 op_sel_hi:[1,0,0] neg_lo:[1,0,0] neg_hi:[1,0,0]
	v_pk_add_f32 v[78:79], v[62:63], v[78:79]
	v_pk_add_f32 v[114:115], v[114:115], 1.0 op_sel_hi:[1,0]
	v_and_b32_e32 v155, 0xffff0000, v72
	v_pk_mul_f32 v[66:67], v[66:67], v[114:115]
	v_pk_fma_f32 v[118:119], v[16:17], v[164:165], v[178:179]
	v_pk_mul_f32 v[66:67], v[78:79], v[66:67]
	v_pk_mul_f32 v[78:79], v[30:31], v[104:105]
	v_cvt_pk_bf16_f32 v84, v66, v67
	v_pk_mul_f32 v[66:67], v[22:23], v[202:203]
	v_pk_fma_f32 v[78:79], v[14:15], v[116:117], v[78:79]
	v_pk_fma_f32 v[66:67], v[6:7], v[120:121], v[66:67]
	v_pk_fma_f32 v[78:79], v[46:47], v[150:151], v[78:79]
	v_pk_fma_f32 v[66:67], v[38:39], v[174:175], v[66:67]
	v_pk_add_f32 v[78:79], v[62:63], v[78:79]
	v_pk_add_f32 v[66:67], v[54:55], v[66:67]
	v_cvt_pk_bf16_f32 v92, v92, v93
	v_mul_f32_e32 v0, 0x3d372713, v66
	v_mul_f32_e32 v0, v66, v0
	v_fma_f32 v0, v66, v0, v66
	v_mul_f32_e32 v0, 0x3f4c422a, v0
	v_add_f32_e32 v0, v0, v0
	v_mul_f32_e32 v0, 0x3fb8aa3b, v0
	v_exp_f32_e32 v0, v0
	v_lshlrev_b32_e32 v178, 16, v77
	v_and_b32_e32 v179, 0xffff0000, v77
	v_lshlrev_b32_e32 v164, 16, v81
	v_add_f32_e32 v0, 1.0, v0
	v_rcp_f32_e32 v114, v0
	v_mul_f32_e32 v0, 0x3d372713, v67
	v_mul_f32_e32 v0, v67, v0
	v_fma_f32 v0, v67, v0, v67
	v_mul_f32_e32 v0, 0x3f4c422a, v0
	v_add_f32_e32 v0, v0, v0
	v_mul_f32_e32 v0, 0x3fb8aa3b, v0
	v_exp_f32_e32 v0, v0
	v_pk_mul_f32 v[66:67], v[66:67], 0.5 op_sel_hi:[1,0]
	v_and_b32_e32 v165, 0xffff0000, v81
	v_pk_mul_f32 v[80:81], v[32:33], v[94:95]
	v_add_f32_e32 v0, 1.0, v0
	v_rcp_f32_e32 v115, v0
	v_pk_fma_f32 v[80:81], v[16:17], v[100:101], v[80:81]
	v_pk_fma_f32 v[114:115], v[114:115], 2.0, 1.0 op_sel_hi:[1,0,0] neg_lo:[1,0,0] neg_hi:[1,0,0]
	s_nop 0
	v_pk_add_f32 v[114:115], v[114:115], 1.0 op_sel_hi:[1,0]
	v_pk_fma_f32 v[80:81], v[48:49], v[164:165], v[80:81]
	v_pk_mul_f32 v[66:67], v[66:67], v[114:115]
	v_pk_mul_f32 v[114:115], v[30:31], v[150:151]
	v_pk_mul_f32 v[66:67], v[78:79], v[66:67]
	v_pk_fma_f32 v[104:105], v[14:15], v[104:105], v[114:115]
	v_cvt_pk_bf16_f32 v76, v66, v67
	v_pk_mul_f32 v[66:67], v[22:23], v[174:175]
	v_pk_fma_f32 v[104:105], v[46:47], v[154:155], v[104:105]
	v_pk_fma_f32 v[66:67], v[6:7], v[202:203], v[66:67]
	v_pk_add_f32 v[104:105], v[62:63], v[104:105]
	v_pk_fma_f32 v[66:67], v[38:39], v[142:143], v[66:67]
	v_pk_fma_f32 v[114:115], v[24:25], v[170:171], v[180:181]
	v_pk_add_f32 v[66:67], v[54:55], v[66:67]
	v_pk_add_f32 v[80:81], v[64:65], v[80:81]
	v_mul_f32_e32 v0, 0x3d372713, v66
	v_mul_f32_e32 v0, v66, v0
	v_fma_f32 v0, v66, v0, v66
	v_mul_f32_e32 v0, 0x3f4c422a, v0
	v_add_f32_e32 v0, v0, v0
	v_mul_f32_e32 v0, 0x3fb8aa3b, v0
	v_exp_f32_e32 v0, v0
	s_nop 0
	v_add_f32_e32 v0, 1.0, v0
	v_rcp_f32_e32 v78, v0
	v_mul_f32_e32 v0, 0x3d372713, v67
	v_mul_f32_e32 v0, v67, v0
	v_fma_f32 v0, v67, v0, v67
	v_mul_f32_e32 v0, 0x3f4c422a, v0
	v_add_f32_e32 v0, v0, v0
	v_mul_f32_e32 v0, 0x3fb8aa3b, v0
	v_exp_f32_e32 v0, v0
	v_pk_mul_f32 v[66:67], v[66:67], 0.5 op_sel_hi:[1,0]
	v_add_f32_e32 v0, 1.0, v0
	v_rcp_f32_e32 v79, v0
	s_nop 0
	v_pk_fma_f32 v[78:79], v[78:79], 2.0, 1.0 op_sel_hi:[1,0,0] neg_lo:[1,0,0] neg_hi:[1,0,0]
	s_nop 0
	v_pk_add_f32 v[78:79], v[78:79], 1.0 op_sel_hi:[1,0]
	s_nop 0
	v_pk_mul_f32 v[66:67], v[66:67], v[78:79]
	s_nop 0
	v_pk_mul_f32 v[78:79], v[104:105], v[66:67]
	v_lshlrev_b32_e32 v104, 16, v85
	v_and_b32_e32 v105, 0xffff0000, v85
	v_pk_fma_f32 v[114:115], v[40:41], v[104:105], v[114:115]
	v_lshlrev_b32_e32 v66, 16, v89
	v_pk_add_f32 v[114:115], v[56:57], v[114:115]
	v_and_b32_e32 v67, 0xffff0000, v89
	v_mul_f32_e32 v0, 0x3d372713, v114
	v_mul_f32_e32 v0, v114, v0
	v_fma_f32 v0, v114, v0, v114
	v_mul_f32_e32 v0, 0x3f4c422a, v0
	v_add_f32_e32 v0, v0, v0
	v_mul_f32_e32 v0, 0x3fb8aa3b, v0
	v_exp_f32_e32 v0, v0
	v_pk_fma_f32 v[118:119], v[48:49], v[66:67], v[118:119]
	v_add_f32_e32 v0, 1.0, v0
	v_rcp_f32_e32 v116, v0
	v_mul_f32_e32 v0, 0x3d372713, v115
	v_mul_f32_e32 v0, v115, v0
	v_fma_f32 v0, v115, v0, v115
	v_mul_f32_e32 v0, 0x3f4c422a, v0
	v_add_f32_e32 v0, v0, v0
	v_mul_f32_e32 v0, 0x3fb8aa3b, v0
	v_exp_f32_e32 v0, v0
	v_pk_mul_f32 v[114:115], v[114:115], 0.5 op_sel_hi:[1,0]
	v_pk_add_f32 v[118:119], v[64:65], v[118:119]
	v_add_f32_e32 v0, 1.0, v0
	v_rcp_f32_e32 v117, v0
	s_nop 0
	v_pk_fma_f32 v[116:117], v[116:117], 2.0, 1.0 op_sel_hi:[1,0,0] neg_lo:[1,0,0] neg_hi:[1,0,0]
	s_nop 0
	v_pk_add_f32 v[116:117], v[116:117], 1.0 op_sel_hi:[1,0]
	s_nop 0
	v_pk_mul_f32 v[114:115], v[114:115], v[116:117]
	s_nop 0
	v_pk_mul_f32 v[114:115], v[118:119], v[114:115]
	s_nop 0
	v_cvt_pk_bf16_f32 v93, v114, v115
	v_add_co_u32_e32 v114, vcc, s92, v176
	s_nop 1
	v_addc_co_u32_e32 v115, vcc, 0, v177, vcc
	global_store_dwordx4 v[114:115], v[90:93], off
	v_pk_mul_f32 v[114:115], v[32:33], v[66:67]
	s_nop 0
	v_pk_mul_f32 v[90:91], v[24:25], v[104:105]
	v_pk_fma_f32 v[114:115], v[16:17], v[172:173], v[114:115]
	v_pk_fma_f32 v[90:91], v[8:9], v[170:171], v[90:91]
	v_pk_fma_f32 v[114:115], v[48:49], v[112:113], v[114:115]
	v_pk_fma_f32 v[90:91], v[40:41], v[108:109], v[90:91]
	v_pk_add_f32 v[114:115], v[64:65], v[114:115]
	v_pk_add_f32 v[90:91], v[56:57], v[90:91]
	v_lshlrev_b32_e32 v170, 16, v69
	v_mul_f32_e32 v0, 0x3d372713, v90
	v_mul_f32_e32 v0, v90, v0
	v_fma_f32 v0, v90, v0, v90
	v_mul_f32_e32 v0, 0x3f4c422a, v0
; DI unsigned pack2(float lo, float hi) { f32x2 v = {lo, hi}; bf2_t b = __builtin_convertvector(v, bf2_t); return __builtin_bit_cast(unsigned, b); }
; DI void unpack8(const u32x4& v, float* f) { f[0] = bflo(v.x); f[1] = bfhi(v.x); f[2] = bflo(v.y); f[3] = bfhi(v.y); f[4] = bflo(v.z); f[5] = bfhi(v.z); f[6] = bflo(v.w); f[7] = bfhi(v.w); }
; DI float gelu_tanh(float x) { const float y = 0.7978845608028654f * (x + 0.044715f * x * x * x); const float t = 1.f - 2.f * __builtin_amdgcn_rcpf(1.f + __expf(2.f * y)); return 0.5f * x * (1.f + t); }
; DI void ffn_act_phase(const Params& P, int l) {
;     ...
;       for (int i = 0; i < 8; ++i) {
;         float g0[8], u0[8]; unpack8(G[i], g0); unpack8(U[i], u0);
;         float o[8];
; #pragma unroll
;         for (int e = 0; e < 8; ++e) { const float yg = wg[0][e] * g2[e] + wg[1][e] * g1[e] + wg[2][e] * g0[e] + bg[e]; const float yu = wu[0][e] * u2[e] + wu[1][e] * u1[e] + wu[2][e] * u0[e] + bu[e];
;           o[e] = gelu_tanh(yg) * yu; g2[e] = g1[e]; g1[e] = g0[e]; u2[e] = u1[e]; u1[e] = u0[e]; }
;         u32x4 pk = {pack2(o[0], o[1]), pack2(o[2], o[3]), pack2(o[4], o[5]), pack2(o[6], o[7])};
;         *(u32x4*)(act + (size_t)(r0 + rb * 8 + i) * DFF + ch) = pk;
;       }
;     }
;   }
	v_add_f32_e32 v0, v0, v0
	v_mul_f32_e32 v0, 0x3fb8aa3b, v0
	v_exp_f32_e32 v0, v0
	v_and_b32_e32 v171, 0xffff0000, v69
	v_lshlrev_b32_e32 v172, 16, v73
	v_and_b32_e32 v173, 0xffff0000, v73
	v_add_f32_e32 v0, 1.0, v0
	v_rcp_f32_e32 v92, v0
	v_mul_f32_e32 v0, 0x3d372713, v91
	v_mul_f32_e32 v0, v91, v0
	v_fma_f32 v0, v91, v0, v91
	v_mul_f32_e32 v0, 0x3f4c422a, v0
	v_add_f32_e32 v0, v0, v0
	v_mul_f32_e32 v0, 0x3fb8aa3b, v0
	v_exp_f32_e32 v0, v0
	v_pk_mul_f32 v[90:91], v[90:91], 0.5 op_sel_hi:[1,0]
	v_pk_mul_f32 v[72:73], v[32:33], v[164:165]
	v_add_f32_e32 v0, 1.0, v0
	v_rcp_f32_e32 v93, v0
	v_pk_fma_f32 v[72:73], v[16:17], v[94:95], v[72:73]
	v_pk_fma_f32 v[92:93], v[92:93], 2.0, 1.0 op_sel_hi:[1,0,0] neg_lo:[1,0,0] neg_hi:[1,0,0]
	s_nop 0
	v_pk_add_f32 v[92:93], v[92:93], 1.0 op_sel_hi:[1,0]
	v_pk_fma_f32 v[72:73], v[48:49], v[172:173], v[72:73]
	v_pk_mul_f32 v[90:91], v[90:91], v[92:93]
	v_pk_add_f32 v[72:73], v[64:65], v[72:73]
	v_pk_mul_f32 v[90:91], v[114:115], v[90:91]
	s_nop 0
	v_cvt_pk_bf16_f32 v89, v90, v91
	v_add_co_u32_e32 v90, vcc, s23, v176
	s_mov_b32 s23, 0x62ed000
	s_nop 0
	v_addc_co_u32_e32 v91, vcc, 0, v177, vcc
	global_store_dwordx4 v[90:91], v[86:89], off offset:3072
	s_nop 1
	v_pk_mul_f32 v[86:87], v[24:25], v[108:109]
	v_pk_mul_f32 v[88:89], v[32:33], v[112:113]
	v_pk_fma_f32 v[86:87], v[8:9], v[104:105], v[86:87]
	v_pk_fma_f32 v[66:67], v[16:17], v[66:67], v[88:89]
	v_pk_fma_f32 v[86:87], v[40:41], v[110:111], v[86:87]
	v_pk_fma_f32 v[66:67], v[48:49], v[106:107], v[66:67]
	v_pk_add_f32 v[86:87], v[56:57], v[86:87]
	v_pk_add_f32 v[66:67], v[64:65], v[66:67]
	v_mul_f32_e32 v0, 0x3d372713, v86
	v_mul_f32_e32 v0, v86, v0
	v_fma_f32 v0, v86, v0, v86
	v_mul_f32_e32 v0, 0x3f4c422a, v0
	v_add_f32_e32 v0, v0, v0
	v_mul_f32_e32 v0, 0x3fb8aa3b, v0
	v_exp_f32_e32 v0, v0
	s_nop 0
	v_add_f32_e32 v0, 1.0, v0
	v_rcp_f32_e32 v90, v0
	v_mul_f32_e32 v0, 0x3d372713, v87
	v_mul_f32_e32 v0, v87, v0
	v_fma_f32 v0, v87, v0, v87
	v_mul_f32_e32 v0, 0x3f4c422a, v0
	v_add_f32_e32 v0, v0, v0
	v_mul_f32_e32 v0, 0x3fb8aa3b, v0
	v_exp_f32_e32 v0, v0
	v_pk_mul_f32 v[86:87], v[86:87], 0.5 op_sel_hi:[1,0]
	v_add_f32_e32 v0, 1.0, v0
	v_rcp_f32_e32 v91, v0
	s_nop 0
	v_pk_fma_f32 v[88:89], v[90:91], 2.0, 1.0 op_sel_hi:[1,0,0] neg_lo:[1,0,0] neg_hi:[1,0,0]
	s_nop 0
	v_pk_add_f32 v[88:89], v[88:89], 1.0 op_sel_hi:[1,0]
	s_nop 0
	v_pk_mul_f32 v[86:87], v[86:87], v[88:89]
	s_nop 0
	v_pk_mul_f32 v[66:67], v[66:67], v[86:87]
	s_nop 0
	v_cvt_pk_bf16_f32 v85, v66, v67
	v_add_co_u32_e32 v66, vcc, s23, v176
	s_mov_b32 s23, 0x62f8000
	s_nop 0
	v_addc_co_u32_e32 v67, vcc, 0, v177, vcc
	global_store_dwordx4 v[66:67], v[82:85], off offset:2048
	v_pk_mul_f32 v[66:67], v[24:25], v[98:99]
	s_nop 0
	v_pk_fma_f32 v[66:67], v[8:9], v[102:103], v[66:67]
	s_nop 0
	v_pk_fma_f32 v[66:67], v[40:41], v[178:179], v[66:67]
	s_nop 0
	v_pk_add_f32 v[66:67], v[56:57], v[66:67]
	s_nop 0
	v_mul_f32_e32 v0, 0x3d372713, v66
	v_mul_f32_e32 v0, v66, v0
	v_fma_f32 v0, v66, v0, v66
	v_mul_f32_e32 v0, 0x3f4c422a, v0
	v_add_f32_e32 v0, v0, v0
	v_mul_f32_e32 v0, 0x3fb8aa3b, v0
	v_exp_f32_e32 v0, v0
	s_nop 0
	v_add_f32_e32 v0, 1.0, v0
	v_rcp_f32_e32 v82, v0
	v_mul_f32_e32 v0, 0x3d372713, v67
	v_mul_f32_e32 v0, v67, v0
	v_fma_f32 v0, v67, v0, v67
	v_mul_f32_e32 v0, 0x3f4c422a, v0
	v_add_f32_e32 v0, v0, v0
	v_mul_f32_e32 v0, 0x3fb8aa3b, v0
	v_exp_f32_e32 v0, v0
	v_pk_mul_f32 v[66:67], v[66:67], 0.5 op_sel_hi:[1,0]
	v_add_f32_e32 v0, 1.0, v0
	v_rcp_f32_e32 v83, v0
	s_nop 0
	v_pk_fma_f32 v[82:83], v[82:83], 2.0, 1.0 op_sel_hi:[1,0,0] neg_lo:[1,0,0] neg_hi:[1,0,0]
	s_nop 0
	v_pk_add_f32 v[82:83], v[82:83], 1.0 op_sel_hi:[1,0]
	s_nop 0
	v_pk_mul_f32 v[66:67], v[66:67], v[82:83]
	s_nop 0
	v_pk_mul_f32 v[66:67], v[80:81], v[66:67]
	s_nop 0
	v_cvt_pk_bf16_f32 v77, v66, v67
	v_add_co_u32_e32 v66, vcc, s23, v176
	s_nop 1
	v_addc_co_u32_e32 v67, vcc, 0, v177, vcc
	global_store_dwordx4 v[66:67], v[74:77], off offset:2048
	v_pk_mul_f32 v[66:67], v[24:25], v[178:179]
	s_nop 0
	v_pk_fma_f32 v[66:67], v[8:9], v[98:99], v[66:67]
	s_nop 0
	v_pk_fma_f32 v[66:67], v[40:41], v[170:171], v[66:67]
	s_nop 0
	v_pk_add_f32 v[66:67], v[56:57], v[66:67]
	s_nop 0
	v_mul_f32_e32 v0, 0x3d372713, v66
	v_mul_f32_e32 v0, v66, v0
	v_fma_f32 v0, v66, v0, v66
	v_mul_f32_e32 v0, 0x3f4c422a, v0
	v_add_f32_e32 v0, v0, v0
	v_mul_f32_e32 v0, 0x3fb8aa3b, v0
	v_exp_f32_e32 v0, v0
	s_nop 0
	v_add_f32_e32 v0, 1.0, v0
	v_rcp_f32_e32 v68, v0
	v_mul_f32_e32 v0, 0x3d372713, v67
	v_mul_f32_e32 v0, v67, v0
	v_fma_f32 v0, v67, v0, v67
	v_mul_f32_e32 v0, 0x3f4c422a, v0
	v_add_f32_e32 v0, v0, v0
	v_mul_f32_e32 v0, 0x3fb8aa3b, v0
	v_exp_f32_e32 v0, v0
	v_pk_mul_f32 v[66:67], v[66:67], 0.5 op_sel_hi:[1,0]
	v_add_f32_e32 v0, 1.0, v0
	v_rcp_f32_e32 v69, v0
	s_nop 0
	v_pk_fma_f32 v[68:69], v[68:69], 2.0, 1.0 op_sel_hi:[1,0,0] neg_lo:[1,0,0] neg_hi:[1,0,0]
	s_nop 0
	v_pk_add_f32 v[68:69], v[68:69], 1.0 op_sel_hi:[1,0]
	s_nop 0
	v_pk_mul_f32 v[66:67], v[66:67], v[68:69]
	v_cvt_pk_bf16_f32 v68, v78, v79
	v_pk_mul_f32 v[72:73], v[72:73], v[66:67]
	v_cvt_pk_bf16_f32 v67, v70, v71
	v_add_co_u32_e32 v70, vcc, 0x62fb000, v176
	v_cvt_pk_bf16_f32 v66, v96, v97
	v_cvt_pk_bf16_f32 v69, v72, v73
	v_addc_co_u32_e32 v71, vcc, 0, v177, vcc
	global_store_dwordx4 v[70:71], v[66:69], off offset:1024
	s_cbranch_scc0 .LBB0_1021
	v_add_u32_e32 v209, s79, v209
	s_movk_i32 s22, 0x15ff
	v_cmp_lt_i32_e32 vcc, s22, v209
	s_or_b64 s[20:21], vcc, s[20:21]
	s_andn2_b64 exec, exec, s[20:21]
	s_cbranch_execnz .LBB0_1018
